# xattn PV: LDS transposed reads software-pipelined (ring of 7, counted lgkmcnt) and output stores widened to dwordx4 via v_permlane32_swap (32 -> 16 stores/lane); plus P4 load hoist and FoX wait deferr
# speedup vs baseline: 1.0111x; 1.0038x over previous
.LBB0_760:
	global_load_dwordx4 v[212:215], v[170:171], off offset:-128
	global_load_dwordx4 v[216:219], v[170:171], off offset:-96
	v_add_u32_e32 v159, s47, v211
	ds_read_b128 v[224:227], v159
	ds_read_b128 v[228:231], v159 offset:32
	v_add_u32_e32 v181, 0x11800, v159
	v_add_u32_e32 v220, 0x15e00, v159
	s_addk_i32 s47, 0x100
	s_cmpk_lg_i32 s47, 0x200
	s_waitcnt vmcnt(1) lgkmcnt(1)
	v_mfma_f32_32x32x16_bf16 v[112:127], v[224:227], v[212:215], v[112:127]
	ds_read_b128 v[224:227], v159 offset:17920
	ds_read_b128 v[232:235], v159 offset:17952
	s_waitcnt lgkmcnt(1)
	v_mfma_f32_32x32x16_bf16 v[96:111], v[224:227], v[212:215], v[96:111]
	ds_read_b128 v[224:227], v159 offset:35840
	ds_read_b128 v[236:239], v159 offset:35872
	ds_read_b128 v[240:243], v159 offset:53792
	s_waitcnt lgkmcnt(2)
	v_mfma_f32_32x32x16_bf16 v[80:95], v[224:227], v[212:215], v[80:95]
	ds_read_b128 v[224:227], v159 offset:53760
	s_waitcnt lgkmcnt(0)
	v_mfma_f32_32x32x16_bf16 v[64:79], v[224:227], v[212:215], v[64:79]
	ds_read_b128 v[224:227], v181
	ds_read_b128 v[244:247], v220
	v_add_u32_e32 v181, 0x1a400, v159
	v_add_u32_e32 v220, 0x1ea00, v159
	s_waitcnt lgkmcnt(1)
	v_mfma_f32_32x32x16_bf16 v[48:63], v[224:227], v[212:215], v[48:63]
	s_waitcnt lgkmcnt(0)
	v_mfma_f32_32x32x16_bf16 v[32:47], v[244:247], v[212:215], v[32:47]
	ds_read_b128 v[224:227], v181
	ds_read_b128 v[244:247], v220
	v_add_u32_e32 v181, 0x11820, v159
	v_add_u32_e32 v220, 0x15e20, v159
	s_waitcnt lgkmcnt(1)
	v_mfma_f32_32x32x16_bf16 v[16:31], v[224:227], v[212:215], v[16:31]
	s_waitcnt lgkmcnt(0)
	v_mfma_f32_32x32x16_bf16 v[0:15], v[244:247], v[212:215], v[0:15]
	ds_read_b128 v[212:215], v181
	ds_read_b128 v[224:227], v220
	v_add_u32_e32 v181, 0x1a420, v159
	v_add_u32_e32 v220, 0x1ea20, v159
	s_waitcnt vmcnt(0) lgkmcnt(1)
	v_mfma_f32_32x32x16_bf16 v[48:63], v[212:215], v[216:219], v[48:63]
	s_waitcnt lgkmcnt(0)
	v_mfma_f32_32x32x16_bf16 v[32:47], v[224:227], v[216:219], v[32:47]
	ds_read_b128 v[212:215], v181
	ds_read_b128 v[224:227], v220
	v_add_u32_e32 v181, 0x11840, v159
	v_add_u32_e32 v220, 0x15e40, v159
	v_mfma_f32_32x32x16_bf16 v[112:127], v[228:231], v[216:219], v[112:127]
	s_waitcnt lgkmcnt(1)
	v_mfma_f32_32x32x16_bf16 v[16:31], v[212:215], v[216:219], v[16:31]
	global_load_dwordx4 v[212:215], v[170:171], off offset:-64
	global_load_dwordx4 v[228:231], v[170:171], off offset:-32
	v_mfma_f32_32x32x16_bf16 v[96:111], v[232:235], v[216:219], v[96:111]
	v_mfma_f32_32x32x16_bf16 v[80:95], v[236:239], v[216:219], v[80:95]
	v_mfma_f32_32x32x16_bf16 v[64:79], v[240:243], v[216:219], v[64:79]
	s_waitcnt lgkmcnt(0)
	v_mfma_f32_32x32x16_bf16 v[0:15], v[224:227], v[216:219], v[0:15]
	ds_read_b128 v[216:219], v159 offset:64
	ds_read_b128 v[224:227], v159 offset:96
	s_waitcnt vmcnt(1) lgkmcnt(1)
	v_mfma_f32_32x32x16_bf16 v[112:127], v[216:219], v[212:215], v[112:127]
	ds_read_b128 v[216:219], v159 offset:17984
	ds_read_b128 v[232:235], v159 offset:18016
	s_waitcnt lgkmcnt(1)
	v_mfma_f32_32x32x16_bf16 v[96:111], v[216:219], v[212:215], v[96:111]
	ds_read_b128 v[216:219], v159 offset:35904
	ds_read_b128 v[236:239], v159 offset:35936
	ds_read_b128 v[240:243], v159 offset:53856
	s_waitcnt lgkmcnt(2)
	v_mfma_f32_32x32x16_bf16 v[80:95], v[216:219], v[212:215], v[80:95]
	ds_read_b128 v[216:219], v159 offset:53824
	s_waitcnt lgkmcnt(0)
	v_mfma_f32_32x32x16_bf16 v[64:79], v[216:219], v[212:215], v[64:79]
	ds_read_b128 v[216:219], v181
	ds_read_b128 v[244:247], v220
	v_add_u32_e32 v181, 0x1a440, v159
	v_add_u32_e32 v220, 0x1ea40, v159
	s_waitcnt lgkmcnt(1)
	v_mfma_f32_32x32x16_bf16 v[48:63], v[216:219], v[212:215], v[48:63]
	s_waitcnt lgkmcnt(0)
	v_mfma_f32_32x32x16_bf16 v[32:47], v[244:247], v[212:215], v[32:47]
	ds_read_b128 v[216:219], v181
	ds_read_b128 v[244:247], v220
	v_add_u32_e32 v181, 0x11860, v159
	v_add_u32_e32 v220, 0x1ea60, v159
	s_waitcnt lgkmcnt(1)
	v_mfma_f32_32x32x16_bf16 v[16:31], v[216:219], v[212:215], v[16:31]
	v_add_u32_e32 v216, 0x15e60, v159
	s_waitcnt lgkmcnt(0)
	v_mfma_f32_32x32x16_bf16 v[0:15], v[244:247], v[212:215], v[0:15]
	ds_read_b128 v[212:215], v181
	ds_read_b128 v[216:219], v216
	v_add_u32_e32 v181, 0x1a460, v159
	s_waitcnt vmcnt(0) lgkmcnt(1)
	v_mfma_f32_32x32x16_bf16 v[48:63], v[212:215], v[228:231], v[48:63]
	s_waitcnt lgkmcnt(0)
	v_mfma_f32_32x32x16_bf16 v[32:47], v[216:219], v[228:231], v[32:47]
	ds_read_b128 v[212:215], v181
	ds_read_b128 v[216:219], v220
	v_add_u32_e32 v181, 0x11880, v159
	v_add_u32_e32 v220, 0x15e80, v159
	v_mfma_f32_32x32x16_bf16 v[112:127], v[224:227], v[228:231], v[112:127]
	s_waitcnt lgkmcnt(1)
	v_mfma_f32_32x32x16_bf16 v[16:31], v[212:215], v[228:231], v[16:31]
	global_load_dwordx4 v[212:215], v[170:171], off
	global_load_dwordx4 v[224:227], v[170:171], off offset:32
	v_mfma_f32_32x32x16_bf16 v[96:111], v[232:235], v[228:231], v[96:111]
	v_mfma_f32_32x32x16_bf16 v[80:95], v[236:239], v[228:231], v[80:95]
	v_mfma_f32_32x32x16_bf16 v[64:79], v[240:243], v[228:231], v[64:79]
	s_waitcnt lgkmcnt(0)
	v_mfma_f32_32x32x16_bf16 v[0:15], v[216:219], v[228:231], v[0:15]
	ds_read_b128 v[216:219], v159 offset:128
	ds_read_b128 v[228:231], v159 offset:160
	s_waitcnt vmcnt(1) lgkmcnt(1)
	v_mfma_f32_32x32x16_bf16 v[112:127], v[216:219], v[212:215], v[112:127]
	ds_read_b128 v[216:219], v159 offset:18048
	ds_read_b128 v[232:235], v159 offset:18080
	s_waitcnt lgkmcnt(1)
	v_mfma_f32_32x32x16_bf16 v[96:111], v[216:219], v[212:215], v[96:111]
	ds_read_b128 v[216:219], v159 offset:35968
	ds_read_b128 v[236:239], v159 offset:36000
	ds_read_b128 v[240:243], v159 offset:53920
	s_waitcnt lgkmcnt(2)
	v_mfma_f32_32x32x16_bf16 v[80:95], v[216:219], v[212:215], v[80:95]
	ds_read_b128 v[216:219], v159 offset:53888
	s_waitcnt lgkmcnt(0)
	v_mfma_f32_32x32x16_bf16 v[64:79], v[216:219], v[212:215], v[64:79]
	ds_read_b128 v[216:219], v181
	ds_read_b128 v[244:247], v220
	v_add_u32_e32 v181, 0x1a480, v159
	v_add_u32_e32 v220, 0x1ea80, v159
	s_waitcnt lgkmcnt(1)
	v_mfma_f32_32x32x16_bf16 v[48:63], v[216:219], v[212:215], v[48:63]
	s_waitcnt lgkmcnt(0)
	v_mfma_f32_32x32x16_bf16 v[32:47], v[244:247], v[212:215], v[32:47]
	ds_read_b128 v[216:219], v181
	ds_read_b128 v[244:247], v220
	v_add_u32_e32 v181, 0x118a0, v159
	v_add_u32_e32 v220, 0x1eaa0, v159
	s_waitcnt lgkmcnt(1)
	v_mfma_f32_32x32x16_bf16 v[16:31], v[216:219], v[212:215], v[16:31]
	v_add_u32_e32 v216, 0x15ea0, v159
	s_waitcnt lgkmcnt(0)
	v_mfma_f32_32x32x16_bf16 v[0:15], v[244:247], v[212:215], v[0:15]
	ds_read_b128 v[212:215], v181
	ds_read_b128 v[216:219], v216
	v_add_u32_e32 v181, 0x1a4a0, v159
	s_waitcnt vmcnt(0) lgkmcnt(1)
	v_mfma_f32_32x32x16_bf16 v[48:63], v[212:215], v[224:227], v[48:63]
	s_waitcnt lgkmcnt(0)
	v_mfma_f32_32x32x16_bf16 v[32:47], v[216:219], v[224:227], v[32:47]
	ds_read_b128 v[212:215], v181
	ds_read_b128 v[216:219], v220
	v_add_u32_e32 v181, 0x118c0, v159
	v_add_u32_e32 v220, 0x15ec0, v159
	v_mfma_f32_32x32x16_bf16 v[112:127], v[228:231], v[224:227], v[112:127]
	s_waitcnt lgkmcnt(1)
	v_mfma_f32_32x32x16_bf16 v[16:31], v[212:215], v[224:227], v[16:31]
	global_load_dwordx4 v[212:215], v[170:171], off offset:64
	global_load_dwordx4 v[228:231], v[170:171], off offset:96
	v_lshl_add_u64 v[170:171], v[170:171], 0, s[14:15]
	v_mfma_f32_32x32x16_bf16 v[96:111], v[232:235], v[224:227], v[96:111]
	v_mfma_f32_32x32x16_bf16 v[80:95], v[236:239], v[224:227], v[80:95]
	v_mfma_f32_32x32x16_bf16 v[64:79], v[240:243], v[224:227], v[64:79]
	s_waitcnt lgkmcnt(0)
	v_mfma_f32_32x32x16_bf16 v[0:15], v[216:219], v[224:227], v[0:15]
	ds_read_b128 v[216:219], v159 offset:192
	ds_read_b128 v[224:227], v159 offset:224
	s_waitcnt vmcnt(1) lgkmcnt(1)
	v_mfma_f32_32x32x16_bf16 v[112:127], v[216:219], v[212:215], v[112:127]
	ds_read_b128 v[216:219], v159 offset:18112
	ds_read_b128 v[232:235], v159 offset:18144
	s_waitcnt lgkmcnt(1)
	v_mfma_f32_32x32x16_bf16 v[96:111], v[216:219], v[212:215], v[96:111]
	ds_read_b128 v[216:219], v159 offset:36032
	ds_read_b128 v[236:239], v159 offset:36064
	ds_read_b128 v[240:243], v159 offset:53984
	s_waitcnt lgkmcnt(2)
	v_mfma_f32_32x32x16_bf16 v[80:95], v[216:219], v[212:215], v[80:95]
	ds_read_b128 v[216:219], v159 offset:53952
	s_waitcnt lgkmcnt(0)
	v_mfma_f32_32x32x16_bf16 v[64:79], v[216:219], v[212:215], v[64:79]
	ds_read_b128 v[216:219], v181
	ds_read_b128 v[244:247], v220
	v_add_u32_e32 v181, 0x1a4c0, v159
	v_add_u32_e32 v220, 0x1eac0, v159
	s_waitcnt lgkmcnt(1)
	v_mfma_f32_32x32x16_bf16 v[48:63], v[216:219], v[212:215], v[48:63]
	s_waitcnt lgkmcnt(0)
	v_mfma_f32_32x32x16_bf16 v[32:47], v[244:247], v[212:215], v[32:47]
	ds_read_b128 v[216:219], v181
	ds_read_b128 v[244:247], v220
	v_add_u32_e32 v181, 0x118e0, v159
	s_waitcnt lgkmcnt(1)
	v_mfma_f32_32x32x16_bf16 v[16:31], v[216:219], v[212:215], v[16:31]
	v_add_u32_e32 v216, 0x15ee0, v159
	s_waitcnt lgkmcnt(0)
	v_mfma_f32_32x32x16_bf16 v[0:15], v[244:247], v[212:215], v[0:15]
	ds_read_b128 v[212:215], v181
	ds_read_b128 v[216:219], v216
	v_add_u32_e32 v181, 0x1a4e0, v159
	v_add_u32_e32 v159, 0x1eae0, v159
	s_waitcnt vmcnt(0) lgkmcnt(1)
	v_mfma_f32_32x32x16_bf16 v[48:63], v[212:215], v[228:231], v[48:63]
	s_waitcnt lgkmcnt(0)
	v_mfma_f32_32x32x16_bf16 v[32:47], v[216:219], v[228:231], v[32:47]
	ds_read_b128 v[212:215], v181
	ds_read_b128 v[216:219], v159
	v_mfma_f32_32x32x16_bf16 v[112:127], v[224:227], v[228:231], v[112:127]
	v_mfma_f32_32x32x16_bf16 v[96:111], v[232:235], v[228:231], v[96:111]
	v_mfma_f32_32x32x16_bf16 v[80:95], v[236:239], v[228:231], v[80:95]
	v_mfma_f32_32x32x16_bf16 v[64:79], v[240:243], v[228:231], v[64:79]
	s_waitcnt lgkmcnt(1)
	v_mfma_f32_32x32x16_bf16 v[16:31], v[212:215], v[228:231], v[16:31]
	s_waitcnt lgkmcnt(0)
	v_mfma_f32_32x32x16_bf16 v[0:15], v[216:219], v[228:231], v[0:15]
	s_cbranch_scc1 .LBB0_760
	v_mov_b32_e32 v170, v145
	v_mov_b32_e32 v171, v146
	v_mov_b32_e32 v145, v147
	v_mov_b32_e32 v146, v141
	v_mov_b32_e32 v147, v142
	v_mov_b32_e32 v141, v143
	v_pk_add_f32 v[144:145], v[170:171], v[144:145]
	v_pk_add_f32 v[140:141], v[146:147], v[140:141]
	v_pk_add_f32 v[144:145], v[144:145], v[144:145] op_sel:[0,1] op_sel_hi:[1,0]
	v_pk_add_f32 v[140:141], v[140:141], v[140:141] op_sel:[0,1] op_sel_hi:[1,0]
	v_add_f32_e32 v136, v136, v137
	v_add_f32_e32 v138, v138, v139
	v_mov_b32_e32 v145, v132
	v_mov_b32_e32 v141, v133
	v_mov_b32_e32 v137, v134
	v_mov_b32_e32 v139, v135
	v_pk_add_f32 v[132:133], v[144:145], v[140:141]
	v_pk_add_f32 v[134:135], v[136:137], v[138:139]
	s_lshl_b32 s10, s46, 1
	v_pk_add_f32 v[132:133], v[132:133], v[134:135]
	v_mov_b32_e32 v159, v149
	v_add_f32_e32 v132, v132, v133
	v_fmamk_f32 v132, v132, 0x3a800000, v180
	v_cmp_gt_f32_e32 vcc, s49, v132
	v_mul_f32_e32 v133, 0x4b800000, v132
	s_add_i32 s51, s51, 1
	v_cndmask_b32_e32 v132, v132, v133, vcc
	v_rsq_f32_e32 v132, v132
	s_nop 0
	v_mul_f32_e32 v133, 0x45800000, v132
	v_cndmask_b32_e32 v134, v132, v133, vcc
	v_mov_b32_e32 v132, v129
	v_mov_b32_e32 v133, v130
	v_mov_b32_e32 v129, v131
	v_pk_add_f32 v[128:129], v[132:133], v[128:129]
	v_and_b32_e32 v131, 64, v178
	v_add_f32_e32 v128, v128, v129
	v_mul_f32_e32 v129, v134, v134
	v_mul_f32_e32 v128, v128, v129
	v_fmamk_f32 v128, v128, 0x3b800000, v180
	v_cmp_gt_f32_e32 vcc, s49, v128
	v_mul_f32_e32 v129, 0x4b800000, v128
	v_add_u32_e32 v131, 64, v131
	v_cndmask_b32_e32 v128, v128, v129, vcc
	v_rsq_f32_e32 v128, v128
	s_nop 0
	v_mul_f32_e32 v129, 0x45800000, v128
	v_cndmask_b32_e32 v128, v128, v129, vcc
	v_max3_f32 v129, v112, s50, v113
	v_max3_f32 v129, v129, v114, v115
	v_max3_f32 v129, v129, v116, v117
	v_max3_f32 v129, v129, v118, v119
	v_max3_f32 v129, v129, v120, v121
	v_max3_f32 v129, v129, v122, v123
	v_max3_f32 v129, v129, v124, v125
	v_max3_f32 v129, v129, v126, v127
	v_max3_f32 v129, v129, v96, v97
	v_max3_f32 v129, v129, v98, v99
	v_max3_f32 v129, v129, v100, v101
	v_max3_f32 v129, v129, v102, v103
	v_max3_f32 v129, v129, v104, v105
	v_max3_f32 v129, v129, v106, v107
	v_max3_f32 v129, v129, v108, v109
	v_max3_f32 v129, v129, v110, v111
	v_max3_f32 v129, v129, v80, v81
	v_max3_f32 v129, v129, v82, v83
	v_max3_f32 v129, v129, v84, v85
	v_max3_f32 v129, v129, v86, v87
	v_max3_f32 v129, v129, v88, v89
	v_max3_f32 v129, v129, v90, v91
	v_max3_f32 v129, v129, v92, v93
	v_max3_f32 v129, v129, v94, v95
	v_max3_f32 v129, v129, v64, v65
	v_max3_f32 v129, v129, v66, v67
	v_max3_f32 v129, v129, v68, v69
	v_max3_f32 v129, v129, v70, v71
	v_max3_f32 v129, v129, v72, v73
	v_max3_f32 v129, v129, v74, v75
	v_max3_f32 v129, v129, v76, v77
	v_max3_f32 v129, v129, v78, v79
	v_max3_f32 v129, v129, v48, v49
	v_max3_f32 v129, v129, v50, v51
	v_max3_f32 v129, v129, v52, v53
	v_max3_f32 v129, v129, v54, v55
	v_max3_f32 v129, v129, v56, v57
	v_max3_f32 v129, v129, v58, v59
	v_max3_f32 v129, v129, v60, v61
	v_max3_f32 v129, v129, v62, v63
	v_max3_f32 v129, v129, v32, v33
	v_max3_f32 v129, v129, v34, v35
	v_max3_f32 v129, v129, v36, v37
	v_max3_f32 v129, v129, v38, v39
	v_max3_f32 v129, v129, v40, v41
	v_max3_f32 v129, v129, v42, v43
	v_max3_f32 v129, v129, v44, v45
	v_max3_f32 v129, v129, v46, v47
	v_max3_f32 v129, v129, v16, v17
	v_max3_f32 v129, v129, v18, v19
	v_max3_f32 v129, v129, v20, v21
	v_max3_f32 v129, v129, v22, v23
	v_max3_f32 v129, v129, v24, v25
	v_max3_f32 v129, v129, v26, v27
	v_max3_f32 v129, v129, v28, v29
	v_max3_f32 v129, v129, v30, v31
	v_max3_f32 v129, v129, v0, v1
	v_max3_f32 v129, v129, v2, v3
	v_max3_f32 v129, v129, v4, v5
	v_max3_f32 v129, v129, v6, v7
	v_max3_f32 v129, v129, v8, v9
	v_max3_f32 v129, v129, v10, v11
	v_mul_f32_e32 v128, v134, v128
	v_max3_f32 v129, v129, v12, v13
	v_max3_f32 v130, v129, v14, v15
	v_mul_f32_e32 v129, 0x3db8aa3b, v128
	v_xor_b32_e32 v128, 32, v178
	v_cmp_lt_i32_e32 vcc, v128, v131
	v_mul_f32_e32 v130, v129, v130
	s_nop 0
	v_cndmask_b32_e32 v128, v178, v128, vcc
	v_lshlrev_b32_e32 v128, 2, v128
	ds_bpermute_b32 v131, v128, v130
	s_waitcnt lgkmcnt(0)
	v_max_f32_e32 v131, v131, v131
	v_max_f32_e32 v130, v130, v131
	v_fma_f32 v112, v129, v112, -v130
	v_exp_f32_e32 v112, v112
	v_fma_f32 v113, v129, v113, -v130
	v_exp_f32_e32 v113, v113
	v_fma_f32 v114, v129, v114, -v130
	v_exp_f32_e32 v114, v114
	v_fma_f32 v115, v129, v115, -v130
	v_exp_f32_e32 v115, v115
	v_fma_f32 v116, v129, v116, -v130
	v_add_f32_e32 v131, 0, v112
	v_exp_f32_e32 v132, v116
	v_add_f32_e32 v131, v113, v131
	v_add_f32_e32 v131, v114, v131
	v_add_f32_e32 v131, v115, v131
	v_fma_f32 v117, v129, v117, -v130
	v_add_f32_e32 v116, v132, v131
	v_exp_f32_e32 v131, v117
	v_fma_f32 v117, v129, v118, -v130
	v_exp_f32_e32 v133, v117
	v_fma_f32 v117, v129, v119, -v130
	v_exp_f32_e32 v119, v117
	v_fma_f32 v117, v129, v120, -v130
	v_exp_f32_e32 v120, v117
	v_fma_f32 v117, v129, v121, -v130
	v_add_f32_e32 v116, v131, v116
	v_exp_f32_e32 v121, v117
	v_fma_f32 v117, v129, v122, -v130
	v_add_f32_e32 v116, v133, v116
	v_exp_f32_e32 v122, v117
	v_fma_f32 v117, v129, v123, -v130
	v_add_f32_e32 v116, v119, v116
	v_exp_f32_e32 v123, v117
	v_fma_f32 v117, v129, v124, -v130
	v_add_f32_e32 v116, v120, v116
	v_exp_f32_e32 v124, v117
	v_fma_f32 v117, v129, v125, -v130
	v_add_f32_e32 v116, v121, v116
	v_exp_f32_e32 v125, v117
	v_fma_f32 v117, v129, v126, -v130
	v_add_f32_e32 v116, v122, v116
	v_exp_f32_e32 v126, v117
	v_fma_f32 v117, v129, v127, -v130
	v_add_f32_e32 v116, v123, v116
	v_exp_f32_e32 v127, v117
	v_fma_f32 v96, v129, v96, -v130
	v_add_f32_e32 v116, v124, v116
	v_exp_f32_e32 v96, v96
	v_fma_f32 v97, v129, v97, -v130
	v_add_f32_e32 v116, v125, v116
	v_exp_f32_e32 v97, v97
	v_fma_f32 v98, v129, v98, -v130
	v_add_f32_e32 v116, v126, v116
	v_exp_f32_e32 v98, v98
	v_fma_f32 v99, v129, v99, -v130
	v_add_f32_e32 v134, v127, v116
	v_exp_f32_e32 v99, v99
	v_fma_f32 v100, v129, v100, -v130
	v_cvt_pk_bf16_f32 v116, v112, v113
	v_cvt_pk_bf16_f32 v112, v120, v121
	v_add_f32_e32 v120, v96, v134
	v_exp_f32_e32 v121, v100
	v_add_f32_e32 v120, v97, v120
	v_add_f32_e32 v120, v98, v120
	v_add_f32_e32 v120, v99, v120
	v_fma_f32 v101, v129, v101, -v130
	v_add_f32_e32 v100, v121, v120
	v_exp_f32_e32 v120, v101
	v_fma_f32 v101, v129, v102, -v130
	v_cvt_pk_bf16_f32 v113, v122, v123
	v_exp_f32_e32 v122, v101
	v_fma_f32 v101, v129, v103, -v130
	v_exp_f32_e32 v103, v101
	v_fma_f32 v101, v129, v104, -v130
	v_exp_f32_e32 v104, v101
	v_fma_f32 v101, v129, v105, -v130
	v_add_f32_e32 v100, v120, v100
	v_exp_f32_e32 v105, v101
	v_fma_f32 v101, v129, v106, -v130
	v_add_f32_e32 v100, v122, v100
	v_exp_f32_e32 v106, v101
	v_fma_f32 v101, v129, v107, -v130
	v_add_f32_e32 v100, v103, v100
	v_exp_f32_e32 v107, v101
	v_fma_f32 v101, v129, v108, -v130
	v_add_f32_e32 v100, v104, v100
	v_exp_f32_e32 v108, v101
	v_fma_f32 v101, v129, v109, -v130
	v_add_f32_e32 v100, v105, v100
	v_exp_f32_e32 v109, v101
	v_fma_f32 v101, v129, v110, -v130
	v_add_f32_e32 v100, v106, v100
	v_exp_f32_e32 v110, v101
	v_fma_f32 v101, v129, v111, -v130
	v_add_f32_e32 v100, v107, v100
	v_exp_f32_e32 v111, v101
	v_fma_f32 v80, v129, v80, -v130
	v_add_f32_e32 v100, v108, v100
	v_exp_f32_e32 v80, v80
	v_fma_f32 v81, v129, v81, -v130
	v_add_f32_e32 v100, v109, v100
	v_exp_f32_e32 v81, v81
	v_fma_f32 v82, v129, v82, -v130
	v_add_f32_e32 v100, v110, v100
	v_exp_f32_e32 v82, v82
	v_fma_f32 v83, v129, v83, -v130
	v_add_f32_e32 v123, v111, v100
	v_exp_f32_e32 v83, v83
	v_fma_f32 v84, v129, v84, -v130
	v_cvt_pk_bf16_f32 v100, v96, v97
	v_cvt_pk_bf16_f32 v96, v104, v105
	v_add_f32_e32 v104, v80, v123
	v_exp_f32_e32 v105, v84
	v_add_f32_e32 v104, v81, v104
	v_add_f32_e32 v104, v82, v104
	v_add_f32_e32 v104, v83, v104
	v_fma_f32 v85, v129, v85, -v130
	v_add_f32_e32 v84, v105, v104
	v_exp_f32_e32 v104, v85
	v_fma_f32 v85, v129, v86, -v130
	v_cvt_pk_bf16_f32 v97, v106, v107
	v_exp_f32_e32 v106, v85
	v_fma_f32 v85, v129, v87, -v130
	v_exp_f32_e32 v87, v85
	v_fma_f32 v85, v129, v88, -v130
	v_exp_f32_e32 v88, v85
	v_fma_f32 v85, v129, v89, -v130
	v_add_f32_e32 v84, v104, v84
	v_exp_f32_e32 v89, v85
	v_fma_f32 v85, v129, v90, -v130
	v_add_f32_e32 v84, v106, v84
	v_exp_f32_e32 v90, v85
	v_fma_f32 v85, v129, v91, -v130
	v_add_f32_e32 v84, v87, v84
	v_exp_f32_e32 v91, v85
	v_fma_f32 v85, v129, v92, -v130
	v_add_f32_e32 v84, v88, v84
	v_exp_f32_e32 v92, v85
	v_fma_f32 v85, v129, v93, -v130
	v_add_f32_e32 v84, v89, v84
	v_exp_f32_e32 v93, v85
	v_fma_f32 v85, v129, v94, -v130
	v_add_f32_e32 v84, v90, v84
	v_exp_f32_e32 v94, v85
	v_fma_f32 v85, v129, v95, -v130
	v_add_f32_e32 v84, v91, v84
	v_exp_f32_e32 v95, v85
	v_fma_f32 v64, v129, v64, -v130
	v_add_f32_e32 v84, v92, v84
	v_exp_f32_e32 v64, v64
	v_fma_f32 v65, v129, v65, -v130
	v_add_f32_e32 v84, v93, v84
	v_exp_f32_e32 v65, v65
	v_fma_f32 v66, v129, v66, -v130
	v_add_f32_e32 v84, v94, v84
	v_exp_f32_e32 v66, v66
	v_fma_f32 v67, v129, v67, -v130
	v_add_f32_e32 v107, v95, v84
	v_exp_f32_e32 v67, v67
	v_fma_f32 v68, v129, v68, -v130
	v_cvt_pk_bf16_f32 v84, v80, v81
	v_cvt_pk_bf16_f32 v80, v88, v89
	v_add_f32_e32 v88, v64, v107
	v_exp_f32_e32 v89, v68
	v_add_f32_e32 v88, v65, v88
	v_add_f32_e32 v88, v66, v88
	v_add_f32_e32 v88, v67, v88
	v_fma_f32 v69, v129, v69, -v130
	v_add_f32_e32 v68, v89, v88
	v_exp_f32_e32 v88, v69
	v_fma_f32 v69, v129, v70, -v130
	v_cvt_pk_bf16_f32 v81, v90, v91
	v_exp_f32_e32 v90, v69
	v_fma_f32 v69, v129, v71, -v130
	v_exp_f32_e32 v71, v69
	v_fma_f32 v69, v129, v72, -v130
	v_exp_f32_e32 v72, v69
	v_fma_f32 v69, v129, v73, -v130
	v_add_f32_e32 v68, v88, v68
	v_exp_f32_e32 v73, v69
	v_fma_f32 v69, v129, v74, -v130
	v_add_f32_e32 v68, v90, v68
	v_exp_f32_e32 v74, v69
	v_fma_f32 v69, v129, v75, -v130
	v_add_f32_e32 v68, v71, v68
	v_exp_f32_e32 v75, v69
	v_fma_f32 v69, v129, v76, -v130
	v_add_f32_e32 v68, v72, v68
	v_exp_f32_e32 v76, v69
	v_fma_f32 v69, v129, v77, -v130
	v_add_f32_e32 v68, v73, v68
	v_exp_f32_e32 v77, v69
	v_fma_f32 v69, v129, v78, -v130
	v_add_f32_e32 v68, v74, v68
	v_exp_f32_e32 v78, v69
	v_fma_f32 v69, v129, v79, -v130
	v_add_f32_e32 v68, v75, v68
	v_exp_f32_e32 v79, v69
	v_fma_f32 v48, v129, v48, -v130
	v_add_f32_e32 v68, v76, v68
	v_exp_f32_e32 v48, v48
	v_fma_f32 v49, v129, v49, -v130
	v_add_f32_e32 v68, v77, v68
	v_exp_f32_e32 v49, v49
	v_fma_f32 v50, v129, v50, -v130
	v_add_f32_e32 v68, v78, v68
	v_exp_f32_e32 v50, v50
	v_fma_f32 v51, v129, v51, -v130
	v_add_f32_e32 v91, v79, v68
	v_exp_f32_e32 v51, v51
	v_fma_f32 v52, v129, v52, -v130
	v_cvt_pk_bf16_f32 v68, v64, v65
	v_cvt_pk_bf16_f32 v64, v72, v73
	v_add_f32_e32 v72, v48, v91
	v_exp_f32_e32 v73, v52
	v_add_f32_e32 v72, v49, v72
	v_add_f32_e32 v72, v50, v72
	v_add_f32_e32 v72, v51, v72
	v_fma_f32 v53, v129, v53, -v130
	v_add_f32_e32 v52, v73, v72
	v_exp_f32_e32 v72, v53
	v_fma_f32 v53, v129, v54, -v130
	v_cvt_pk_bf16_f32 v65, v74, v75
	v_exp_f32_e32 v74, v53
	v_fma_f32 v53, v129, v55, -v130
	v_exp_f32_e32 v55, v53
	v_fma_f32 v53, v129, v56, -v130
	v_exp_f32_e32 v56, v53
	v_fma_f32 v53, v129, v57, -v130
	v_add_f32_e32 v52, v72, v52
	v_exp_f32_e32 v57, v53
	v_fma_f32 v53, v129, v58, -v130
	v_add_f32_e32 v52, v74, v52
	v_exp_f32_e32 v58, v53
	v_fma_f32 v53, v129, v59, -v130
	v_add_f32_e32 v52, v55, v52
	v_exp_f32_e32 v59, v53
	v_fma_f32 v53, v129, v60, -v130
	v_add_f32_e32 v52, v56, v52
	v_exp_f32_e32 v60, v53
	v_fma_f32 v53, v129, v61, -v130
	v_add_f32_e32 v52, v57, v52
	v_exp_f32_e32 v61, v53
	v_fma_f32 v53, v129, v62, -v130
	v_add_f32_e32 v52, v58, v52
	v_exp_f32_e32 v62, v53
	v_fma_f32 v53, v129, v63, -v130
	v_add_f32_e32 v52, v59, v52
	v_exp_f32_e32 v63, v53
	v_fma_f32 v32, v129, v32, -v130
	v_add_f32_e32 v52, v60, v52
	v_exp_f32_e32 v32, v32
	v_fma_f32 v33, v129, v33, -v130
	v_add_f32_e32 v52, v61, v52
	v_exp_f32_e32 v33, v33
	v_fma_f32 v34, v129, v34, -v130
	v_add_f32_e32 v52, v62, v52
	v_exp_f32_e32 v34, v34
	v_fma_f32 v35, v129, v35, -v130
	v_add_f32_e32 v75, v63, v52
	v_exp_f32_e32 v35, v35
	v_fma_f32 v36, v129, v36, -v130
	v_cvt_pk_bf16_f32 v52, v48, v49
	v_cvt_pk_bf16_f32 v48, v56, v57
	v_add_f32_e32 v56, v32, v75
	v_exp_f32_e32 v57, v36
	v_add_f32_e32 v56, v33, v56
	v_add_f32_e32 v56, v34, v56
	v_add_f32_e32 v56, v35, v56
	v_fma_f32 v37, v129, v37, -v130
	v_add_f32_e32 v36, v57, v56
	v_exp_f32_e32 v56, v37
	v_fma_f32 v37, v129, v38, -v130
	v_cvt_pk_bf16_f32 v49, v58, v59
	v_exp_f32_e32 v58, v37
	v_fma_f32 v37, v129, v39, -v130
	v_exp_f32_e32 v39, v37
	v_fma_f32 v37, v129, v40, -v130
	v_exp_f32_e32 v40, v37
	v_fma_f32 v37, v129, v41, -v130
	v_add_f32_e32 v36, v56, v36
	v_exp_f32_e32 v41, v37
	v_fma_f32 v37, v129, v42, -v130
	v_add_f32_e32 v36, v58, v36
	v_exp_f32_e32 v42, v37
	v_fma_f32 v37, v129, v43, -v130
	v_add_f32_e32 v36, v39, v36
	v_exp_f32_e32 v43, v37
	v_fma_f32 v37, v129, v44, -v130
	v_add_f32_e32 v36, v40, v36
	v_exp_f32_e32 v44, v37
	v_fma_f32 v37, v129, v45, -v130
	v_add_f32_e32 v36, v41, v36
	v_exp_f32_e32 v45, v37
	v_fma_f32 v37, v129, v46, -v130
	v_add_f32_e32 v36, v42, v36
	v_exp_f32_e32 v46, v37
	v_fma_f32 v37, v129, v47, -v130
	v_add_f32_e32 v36, v43, v36
	v_exp_f32_e32 v47, v37
	v_fma_f32 v16, v129, v16, -v130
	v_add_f32_e32 v36, v44, v36
	v_exp_f32_e32 v16, v16
	v_fma_f32 v17, v129, v17, -v130
	v_add_f32_e32 v36, v45, v36
	v_exp_f32_e32 v17, v17
	v_fma_f32 v18, v129, v18, -v130
	v_add_f32_e32 v36, v46, v36
	v_exp_f32_e32 v18, v18
	v_fma_f32 v19, v129, v19, -v130
	v_add_f32_e32 v59, v47, v36
	v_exp_f32_e32 v19, v19
	v_fma_f32 v20, v129, v20, -v130
	v_cvt_pk_bf16_f32 v36, v32, v33
	v_cvt_pk_bf16_f32 v32, v40, v41
	v_add_f32_e32 v40, v16, v59
	v_exp_f32_e32 v41, v20
	v_add_f32_e32 v40, v17, v40
	v_add_f32_e32 v40, v18, v40
	v_add_f32_e32 v40, v19, v40
	v_fma_f32 v21, v129, v21, -v130
	v_add_f32_e32 v20, v41, v40
	v_exp_f32_e32 v40, v21
	v_fma_f32 v21, v129, v22, -v130
	v_cvt_pk_bf16_f32 v33, v42, v43
	v_exp_f32_e32 v42, v21
	v_fma_f32 v21, v129, v23, -v130
	v_exp_f32_e32 v23, v21
	v_fma_f32 v21, v129, v24, -v130
	v_exp_f32_e32 v24, v21
	v_fma_f32 v21, v129, v25, -v130
	v_add_f32_e32 v20, v40, v20
	v_exp_f32_e32 v25, v21
	v_fma_f32 v21, v129, v26, -v130
	v_add_f32_e32 v20, v42, v20
	v_exp_f32_e32 v26, v21
	v_fma_f32 v21, v129, v27, -v130
	v_add_f32_e32 v20, v23, v20
	v_exp_f32_e32 v27, v21
	v_fma_f32 v21, v129, v28, -v130
	v_add_f32_e32 v20, v24, v20
	v_exp_f32_e32 v28, v21
	v_fma_f32 v21, v129, v29, -v130
	v_add_f32_e32 v20, v25, v20
	v_exp_f32_e32 v29, v21
	v_fma_f32 v21, v129, v30, -v130
	v_add_f32_e32 v20, v26, v20
	v_exp_f32_e32 v30, v21
	v_fma_f32 v21, v129, v31, -v130
	v_add_f32_e32 v20, v27, v20
	v_exp_f32_e32 v31, v21
	v_fma_f32 v0, v129, v0, -v130
	v_add_f32_e32 v20, v28, v20
	v_exp_f32_e32 v0, v0
	v_fma_f32 v1, v129, v1, -v130
	v_add_f32_e32 v20, v29, v20
	v_exp_f32_e32 v1, v1
	v_fma_f32 v2, v129, v2, -v130
	v_add_f32_e32 v20, v30, v20
	v_exp_f32_e32 v2, v2
	v_fma_f32 v3, v129, v3, -v130
	v_add_f32_e32 v43, v31, v20
	v_exp_f32_e32 v3, v3
	v_fma_f32 v4, v129, v4, -v130
	v_cvt_pk_bf16_f32 v20, v16, v17
	v_cvt_pk_bf16_f32 v16, v24, v25
	v_add_f32_e32 v24, v0, v43
	v_exp_f32_e32 v4, v4
	v_fma_f32 v5, v129, v5, -v130
	v_add_f32_e32 v24, v1, v24
	v_exp_f32_e32 v5, v5
	v_fma_f32 v6, v129, v6, -v130
	v_add_f32_e32 v24, v2, v24
	v_exp_f32_e32 v6, v6
	v_fma_f32 v7, v129, v7, -v130
	v_add_f32_e32 v24, v3, v24
	v_exp_f32_e32 v7, v7
	v_fma_f32 v8, v129, v8, -v130
	v_add_f32_e32 v24, v4, v24
	v_exp_f32_e32 v8, v8
	v_fma_f32 v9, v129, v9, -v130
	v_add_f32_e32 v24, v5, v24
	v_exp_f32_e32 v9, v9
	v_fma_f32 v10, v129, v10, -v130
	v_add_f32_e32 v24, v6, v24
	v_exp_f32_e32 v10, v10
	v_fma_f32 v11, v129, v11, -v130
	v_add_f32_e32 v24, v7, v24
	v_exp_f32_e32 v11, v11
	v_fma_f32 v12, v129, v12, -v130
	v_add_f32_e32 v24, v8, v24
	v_exp_f32_e32 v12, v12
	v_fma_f32 v13, v129, v13, -v130
	v_add_f32_e32 v24, v9, v24
	v_exp_f32_e32 v13, v13
	v_fma_f32 v14, v129, v14, -v130
	v_add_f32_e32 v24, v10, v24
	v_exp_f32_e32 v14, v14
	v_fma_f32 v15, v129, v15, -v130
	v_add_f32_e32 v24, v11, v24
	v_exp_f32_e32 v15, v15
	v_add_f32_e32 v24, v12, v24
	v_add_f32_e32 v24, v13, v24
	v_add_f32_e32 v24, v14, v24
	v_cvt_pk_bf16_f32 v22, v41, v40
	v_add_f32_e32 v40, v15, v24
	v_cvt_pk_bf16_f32 v21, v18, v19
	v_cvt_pk_bf16_f32 v18, v28, v29
	v_cvt_pk_bf16_f32 v28, v0, v1
	ds_bpermute_b32 v0, v128, v40
	v_cvt_pk_bf16_f32 v117, v114, v115
	v_cvt_pk_bf16_f32 v118, v132, v131
	v_cvt_pk_bf16_f32 v119, v133, v119
	v_cvt_pk_bf16_f32 v114, v124, v125
	v_cvt_pk_bf16_f32 v115, v126, v127
	v_cvt_pk_bf16_f32 v101, v98, v99
	v_cvt_pk_bf16_f32 v102, v121, v120
	v_cvt_pk_bf16_f32 v103, v122, v103
	v_cvt_pk_bf16_f32 v98, v108, v109
	v_cvt_pk_bf16_f32 v99, v110, v111
	v_cvt_pk_bf16_f32 v85, v82, v83
	v_cvt_pk_bf16_f32 v86, v105, v104
	v_cvt_pk_bf16_f32 v87, v106, v87
	v_cvt_pk_bf16_f32 v82, v92, v93
	v_cvt_pk_bf16_f32 v83, v94, v95
	v_cvt_pk_bf16_f32 v69, v66, v67
	v_cvt_pk_bf16_f32 v70, v89, v88
	v_cvt_pk_bf16_f32 v71, v90, v71
	v_cvt_pk_bf16_f32 v66, v76, v77
	v_cvt_pk_bf16_f32 v67, v78, v79
	v_cvt_pk_bf16_f32 v53, v50, v51
	v_cvt_pk_bf16_f32 v54, v73, v72
	v_cvt_pk_bf16_f32 v55, v74, v55
	v_cvt_pk_bf16_f32 v50, v60, v61
	v_cvt_pk_bf16_f32 v51, v62, v63
	v_cvt_pk_bf16_f32 v37, v34, v35
	v_cvt_pk_bf16_f32 v38, v57, v56
	v_cvt_pk_bf16_f32 v39, v58, v39
	v_cvt_pk_bf16_f32 v34, v44, v45
	v_cvt_pk_bf16_f32 v35, v46, v47
	v_cvt_pk_bf16_f32 v23, v42, v23
	v_cvt_pk_bf16_f32 v17, v26, v27
	v_cvt_pk_bf16_f32 v19, v30, v31
	v_cvt_pk_bf16_f32 v29, v2, v3
	v_cvt_pk_bf16_f32 v30, v4, v5
	v_cvt_pk_bf16_f32 v31, v6, v7
	v_cvt_pk_bf16_f32 v24, v8, v9
	v_cvt_pk_bf16_f32 v25, v10, v11
	v_cvt_pk_bf16_f32 v26, v12, v13
	v_cvt_pk_bf16_f32 v27, v14, v15
	v_lshl_add_u64 v[60:61], v[160:161], 0, s[38:39]
	s_waitcnt lgkmcnt(0)
	v_add_f32_e32 v72, v40, v0
	s_barrier
	global_load_dwordx4 v[0:3], v[160:161], off offset:2096
	global_load_dwordx4 v[4:7], v[160:161], off offset:2080
	global_load_dwordx4 v[8:11], v[160:161], off offset:2064
	global_load_dwordx4 v[12:15], v[160:161], off offset:2048
	global_load_dwordx4 v[40:43], v[168:169], off offset:2048
	global_load_dwordx4 v[44:47], v[60:61], off offset:48
	global_load_dwordx4 v[56:59], v[60:61], off offset:32
	s_nop 0
	global_load_dwordx4 v[60:63], v[60:61], off offset:16
	s_waitcnt vmcnt(4)
	ds_write_b128 v172, v[12:15]
	ds_write_b128 v172, v[8:11] offset:16
	ds_write_b128 v172, v[4:7] offset:32
	ds_write_b128 v172, v[0:3] offset:48
	s_waitcnt vmcnt(3)
	ds_write_b128 v172, v[40:43] offset:35840
	s_waitcnt vmcnt(0)
	ds_write_b128 v172, v[60:63] offset:35856
	ds_write_b128 v172, v[56:59] offset:35872
	ds_write_b128 v172, v[44:47] offset:35888
	v_lshl_add_u64 v[12:13], v[160:161], 0, s[40:41]
	v_lshl_add_u64 v[60:61], v[160:161], 0, s[44:45]
	global_load_dwordx4 v[0:3], v[164:165], off offset:2048
	global_load_dwordx4 v[4:7], v[12:13], off offset:48
	global_load_dwordx4 v[8:11], v[12:13], off offset:32
	s_nop 0
	global_load_dwordx4 v[12:15], v[12:13], off offset:16
	s_nop 0
	global_load_dwordx4 v[40:43], v[166:167], off offset:2048
	global_load_dwordx4 v[44:47], v[60:61], off offset:48
	global_load_dwordx4 v[56:59], v[60:61], off offset:32
	s_nop 0
	global_load_dwordx4 v[60:63], v[60:61], off offset:16
	s_waitcnt vmcnt(7)
	ds_write_b128 v173, v[0:3]
	s_waitcnt vmcnt(4)
	ds_write_b128 v174, v[12:15]
	ds_write_b128 v175, v[8:11]
	ds_write_b128 v179, v[4:7]
	s_waitcnt vmcnt(3)
	ds_write_b128 v182, v[40:43]
	s_waitcnt vmcnt(0)
	ds_write_b128 v183, v[60:63]
	ds_write_b128 v184, v[56:59]
	ds_write_b128 v185, v[44:47]
	v_div_scale_f32 v0, s[4:5], v72, v72, 1.0
	v_rcp_f32_e32 v1, v0
	s_waitcnt lgkmcnt(0)
	s_barrier
	v_fma_f32 v2, -v0, v1, 1.0
	v_fmac_f32_e32 v1, v2, v1
	v_div_scale_f32 v2, vcc, 1.0, v72, 1.0
	v_mul_f32_e32 v3, v2, v1
	v_fma_f32 v4, -v0, v3, v2
	v_fmac_f32_e32 v3, v4, v1
	v_fma_f32 v0, -v0, v3, v2
	v_div_fmas_f32 v0, v0, v1, v3
	v_div_fixup_f32 v44, v0, v72, 1.0
	v_lshl_add_u64 v[0:1], s[12:13], 0, v[162:163]
	v_lshl_add_u64 v[0:1], v[0:1], 0, s[10:11]
	v_lshl_add_u64 v[46:47], v[0:1], 0, v[158:159]
	v_mbcnt_lo_u32_b32 v40, -1, 0
	v_mbcnt_hi_u32_b32 v40, -1, v40
	v_and_b32_e32 v40, 32, v40
	v_lshrrev_b32_e32 v40, 2, v40
	v_mov_b32_e32 v41, 0
	v_lshl_add_u64 v[124:125], v[46:47], 0, v[40:41]
	ds_read_b64_tr_b16 v[56:57], v186
	ds_read_b64_tr_b16 v[58:59], v186 offset:4480
	ds_read_b64_tr_b16 v[60:61], v186 offset:8960
	ds_read_b64_tr_b16 v[62:63], v186 offset:13440
	ds_read_b64_tr_b16 v[88:89], v186 offset:17920
	ds_read_b64_tr_b16 v[90:91], v186 offset:22400
	ds_read_b64_tr_b16 v[92:93], v186 offset:26880
	ds_read_b64_tr_b16 v[94:95], v186 offset:31360
	ds_read_b64_tr_b16 v[104:105], v186 offset:35840
	ds_read_b64_tr_b16 v[106:107], v186 offset:40320
	ds_read_b64_tr_b16 v[108:109], v186 offset:44800
	ds_read_b64_tr_b16 v[110:111], v186 offset:49280
	ds_read_b64_tr_b16 v[120:121], v186 offset:53760
	ds_read_b64_tr_b16 v[122:123], v186 offset:58240
	s_mov_b64 s[4:5], 0
	s_waitcnt lgkmcnt(12)
	v_mfma_f32_32x32x16_bf16 v[0:15], v[56:59], v[116:119], 0
	v_add_u32_e32 v40, v187, v177
	ds_read_b64_tr_b16 v[56:57], v186 offset:62720
	ds_read_b64_tr_b16 v[58:59], v40
	s_waitcnt lgkmcnt(12)
	v_mfma_f32_32x32x16_bf16 v[0:15], v[60:63], v[112:115], v[0:15]
	v_add_u32_e32 v40, v188, v177
	v_add_u32_e32 v42, v189, v177
	ds_read_b64_tr_b16 v[60:61], v40
	ds_read_b64_tr_b16 v[62:63], v42
	s_waitcnt lgkmcnt(12)
	v_mfma_f32_32x32x16_bf16 v[0:15], v[88:91], v[100:103], v[0:15]
	v_add_u32_e32 v40, v190, v177
	v_add_u32_e32 v42, v191, v177
	ds_read_b64_tr_b16 v[88:89], v40
	ds_read_b64_tr_b16 v[90:91], v42
	s_waitcnt lgkmcnt(12)
	v_mfma_f32_32x32x16_bf16 v[0:15], v[92:95], v[96:99], v[0:15]
	v_add_u32_e32 v40, v192, v177
	v_add_u32_e32 v42, v193, v177
	ds_read_b64_tr_b16 v[92:93], v40
	ds_read_b64_tr_b16 v[94:95], v42
	s_waitcnt lgkmcnt(12)
	v_mfma_f32_32x32x16_bf16 v[0:15], v[104:107], v[84:87], v[0:15]
	v_add_u32_e32 v40, v194, v177
	v_add_u32_e32 v42, v195, v177
	ds_read_b64_tr_b16 v[104:105], v40
	ds_read_b64_tr_b16 v[106:107], v42
	s_waitcnt lgkmcnt(12)
	v_mfma_f32_32x32x16_bf16 v[0:15], v[108:111], v[80:83], v[0:15]
	v_add_u32_e32 v40, v196, v177
	v_add_u32_e32 v42, v197, v177
	ds_read_b64_tr_b16 v[108:109], v40
	ds_read_b64_tr_b16 v[110:111], v42
	s_waitcnt lgkmcnt(12)
	v_mfma_f32_32x32x16_bf16 v[0:15], v[120:123], v[68:71], v[0:15]
	v_add_u32_e32 v40, v198, v177
	v_add_u32_e32 v42, v199, v177
	ds_read_b64_tr_b16 v[120:121], v40
	ds_read_b64_tr_b16 v[122:123], v42
	s_waitcnt lgkmcnt(12)
	v_mfma_f32_32x32x16_bf16 v[0:15], v[56:59], v[64:67], v[0:15]
	v_add_u32_e32 v40, v200, v177
	v_add_u32_e32 v42, v201, v177
	ds_read_b64_tr_b16 v[56:57], v40
	ds_read_b64_tr_b16 v[58:59], v42
	s_waitcnt lgkmcnt(12)
	v_mfma_f32_32x32x16_bf16 v[0:15], v[60:63], v[52:55], v[0:15]
	v_add_u32_e32 v40, v202, v177
	v_add_u32_e32 v42, v203, v177
	ds_read_b64_tr_b16 v[60:61], v40
	ds_read_b64_tr_b16 v[62:63], v42
	s_waitcnt lgkmcnt(12)
	v_mfma_f32_32x32x16_bf16 v[0:15], v[88:91], v[48:51], v[0:15]
	ds_read_b64_tr_b16 v[88:89], v186 offset:64
	ds_read_b64_tr_b16 v[90:91], v186 offset:4544
	s_waitcnt lgkmcnt(12)
	v_mfma_f32_32x32x16_bf16 v[0:15], v[92:95], v[36:39], v[0:15]
	ds_read_b64_tr_b16 v[92:93], v186 offset:9024
	ds_read_b64_tr_b16 v[94:95], v186 offset:13504
	s_waitcnt lgkmcnt(12)
	v_mfma_f32_32x32x16_bf16 v[0:15], v[104:107], v[32:35], v[0:15]
	ds_read_b64_tr_b16 v[104:105], v186 offset:17984
	ds_read_b64_tr_b16 v[106:107], v186 offset:22464
	s_waitcnt lgkmcnt(12)
	v_mfma_f32_32x32x16_bf16 v[0:15], v[108:111], v[20:23], v[0:15]
	ds_read_b64_tr_b16 v[108:109], v186 offset:26944
	ds_read_b64_tr_b16 v[110:111], v186 offset:31424
	s_waitcnt lgkmcnt(12)
	v_mfma_f32_32x32x16_bf16 v[0:15], v[120:123], v[16:19], v[0:15]
	ds_read_b64_tr_b16 v[120:121], v186 offset:35904
	ds_read_b64_tr_b16 v[122:123], v186 offset:40384
	s_waitcnt lgkmcnt(12)
	v_mfma_f32_32x32x16_bf16 v[0:15], v[56:59], v[28:31], v[0:15]
	ds_read_b64_tr_b16 v[56:57], v186 offset:44864
	ds_read_b64_tr_b16 v[58:59], v186 offset:49344
	s_waitcnt lgkmcnt(12)
	v_mfma_f32_32x32x16_bf16 v[0:15], v[60:63], v[24:27], v[0:15]
	ds_read_b64_tr_b16 v[60:61], v186 offset:53824
	ds_read_b64_tr_b16 v[62:63], v186 offset:58304
	s_nop 11
	v_pk_mul_f32 v[0:1], v[0:1], v[44:45] op_sel_hi:[1,0]
	v_pk_mul_f32 v[2:3], v[2:3], v[44:45] op_sel_hi:[1,0]
	v_pk_mul_f32 v[4:5], v[4:5], v[44:45] op_sel_hi:[1,0]
	v_pk_mul_f32 v[6:7], v[6:7], v[44:45] op_sel_hi:[1,0]
	v_cvt_pk_bf16_f32 v0, v0, v1
	v_cvt_pk_bf16_f32 v1, v2, v3
	v_cvt_pk_bf16_f32 v2, v4, v5
	v_cvt_pk_bf16_f32 v3, v6, v7
	s_nop 1
	v_permlane32_swap_b32_e32 v0, v2
	v_permlane32_swap_b32_e32 v1, v3
	global_store_dwordx4 v[124:125], v[0:3], off
	v_pk_mul_f32 v[8:9], v[8:9], v[44:45] op_sel_hi:[1,0]
	v_pk_mul_f32 v[10:11], v[10:11], v[44:45] op_sel_hi:[1,0]
	v_pk_mul_f32 v[12:13], v[12:13], v[44:45] op_sel_hi:[1,0]
	v_pk_mul_f32 v[14:15], v[14:15], v[44:45] op_sel_hi:[1,0]
	v_cvt_pk_bf16_f32 v4, v8, v9
	v_cvt_pk_bf16_f32 v5, v10, v11
	v_cvt_pk_bf16_f32 v6, v12, v13
	v_cvt_pk_bf16_f32 v7, v14, v15
	s_nop 1
	v_permlane32_swap_b32_e32 v4, v6
	v_permlane32_swap_b32_e32 v5, v7
	global_store_dwordx4 v[124:125], v[4:7], off offset:32
	s_nop 1
	s_waitcnt lgkmcnt(12)
	v_mfma_f32_32x32x16_bf16 v[0:15], v[88:91], v[116:119], 0
	v_add_u32_e32 v40, v187, v204
	ds_read_b64_tr_b16 v[88:89], v186 offset:62784
	ds_read_b64_tr_b16 v[90:91], v40
	s_waitcnt lgkmcnt(12)
	v_mfma_f32_32x32x16_bf16 v[0:15], v[92:95], v[112:115], v[0:15]
	v_add_u32_e32 v40, v188, v204
	v_add_u32_e32 v42, v189, v204
	ds_read_b64_tr_b16 v[92:93], v40
	ds_read_b64_tr_b16 v[94:95], v42
	s_waitcnt lgkmcnt(12)
	v_mfma_f32_32x32x16_bf16 v[0:15], v[104:107], v[100:103], v[0:15]
	v_add_u32_e32 v40, v190, v204
	v_add_u32_e32 v42, v191, v204
	ds_read_b64_tr_b16 v[104:105], v40
	ds_read_b64_tr_b16 v[106:107], v42
	s_waitcnt lgkmcnt(12)
	v_mfma_f32_32x32x16_bf16 v[0:15], v[108:111], v[96:99], v[0:15]
	v_add_u32_e32 v40, v192, v204
	v_add_u32_e32 v42, v193, v204
	ds_read_b64_tr_b16 v[108:109], v40
	ds_read_b64_tr_b16 v[110:111], v42
	s_waitcnt lgkmcnt(12)
	v_mfma_f32_32x32x16_bf16 v[0:15], v[120:123], v[84:87], v[0:15]
	v_add_u32_e32 v40, v194, v204
	v_add_u32_e32 v42, v195, v204
	ds_read_b64_tr_b16 v[120:121], v40
	ds_read_b64_tr_b16 v[122:123], v42
	s_waitcnt lgkmcnt(12)
	v_mfma_f32_32x32x16_bf16 v[0:15], v[56:59], v[80:83], v[0:15]
	v_add_u32_e32 v40, v196, v204
	v_add_u32_e32 v42, v197, v204
	ds_read_b64_tr_b16 v[56:57], v40
	ds_read_b64_tr_b16 v[58:59], v42
	s_waitcnt lgkmcnt(12)
	v_mfma_f32_32x32x16_bf16 v[0:15], v[60:63], v[68:71], v[0:15]
	v_add_u32_e32 v40, v198, v204
	v_add_u32_e32 v42, v199, v204
	ds_read_b64_tr_b16 v[60:61], v40
	ds_read_b64_tr_b16 v[62:63], v42
	s_waitcnt lgkmcnt(12)
	v_mfma_f32_32x32x16_bf16 v[0:15], v[88:91], v[64:67], v[0:15]
	v_add_u32_e32 v40, v200, v204
	v_add_u32_e32 v42, v201, v204
	ds_read_b64_tr_b16 v[88:89], v40
	ds_read_b64_tr_b16 v[90:91], v42
	s_waitcnt lgkmcnt(12)
	v_mfma_f32_32x32x16_bf16 v[0:15], v[92:95], v[52:55], v[0:15]
	v_add_u32_e32 v40, v202, v204
	v_add_u32_e32 v42, v203, v204
	ds_read_b64_tr_b16 v[92:93], v40
	ds_read_b64_tr_b16 v[94:95], v42
	s_waitcnt lgkmcnt(12)
	v_mfma_f32_32x32x16_bf16 v[0:15], v[104:107], v[48:51], v[0:15]
	ds_read_b64_tr_b16 v[104:105], v186 offset:128
	ds_read_b64_tr_b16 v[106:107], v186 offset:4608
	s_waitcnt lgkmcnt(12)
	v_mfma_f32_32x32x16_bf16 v[0:15], v[108:111], v[36:39], v[0:15]
	ds_read_b64_tr_b16 v[108:109], v186 offset:9088
	ds_read_b64_tr_b16 v[110:111], v186 offset:13568
	s_waitcnt lgkmcnt(12)
	v_mfma_f32_32x32x16_bf16 v[0:15], v[120:123], v[32:35], v[0:15]
	ds_read_b64_tr_b16 v[120:121], v186 offset:18048
	ds_read_b64_tr_b16 v[122:123], v186 offset:22528
	s_waitcnt lgkmcnt(12)
	v_mfma_f32_32x32x16_bf16 v[0:15], v[56:59], v[20:23], v[0:15]
	ds_read_b64_tr_b16 v[56:57], v186 offset:27008
	ds_read_b64_tr_b16 v[58:59], v186 offset:31488
	s_waitcnt lgkmcnt(12)
	v_mfma_f32_32x32x16_bf16 v[0:15], v[60:63], v[16:19], v[0:15]
	ds_read_b64_tr_b16 v[60:61], v186 offset:35968
	ds_read_b64_tr_b16 v[62:63], v186 offset:40448
	s_waitcnt lgkmcnt(12)
	v_mfma_f32_32x32x16_bf16 v[0:15], v[88:91], v[28:31], v[0:15]
	ds_read_b64_tr_b16 v[88:89], v186 offset:44928
	ds_read_b64_tr_b16 v[90:91], v186 offset:49408
	s_waitcnt lgkmcnt(12)
	v_mfma_f32_32x32x16_bf16 v[0:15], v[92:95], v[24:27], v[0:15]
	ds_read_b64_tr_b16 v[92:93], v186 offset:53888
	ds_read_b64_tr_b16 v[94:95], v186 offset:58368
	s_nop 11
	v_pk_mul_f32 v[0:1], v[0:1], v[44:45] op_sel_hi:[1,0]
	v_pk_mul_f32 v[2:3], v[2:3], v[44:45] op_sel_hi:[1,0]
	v_pk_mul_f32 v[4:5], v[4:5], v[44:45] op_sel_hi:[1,0]
	v_pk_mul_f32 v[6:7], v[6:7], v[44:45] op_sel_hi:[1,0]
	v_cvt_pk_bf16_f32 v0, v0, v1
	v_cvt_pk_bf16_f32 v1, v2, v3
	v_cvt_pk_bf16_f32 v2, v4, v5
	v_cvt_pk_bf16_f32 v3, v6, v7
	s_nop 1
	v_permlane32_swap_b32_e32 v0, v2
	v_permlane32_swap_b32_e32 v1, v3
	global_store_dwordx4 v[124:125], v[0:3], off offset:64
	v_pk_mul_f32 v[8:9], v[8:9], v[44:45] op_sel_hi:[1,0]
	v_pk_mul_f32 v[10:11], v[10:11], v[44:45] op_sel_hi:[1,0]
	v_pk_mul_f32 v[12:13], v[12:13], v[44:45] op_sel_hi:[1,0]
	v_pk_mul_f32 v[14:15], v[14:15], v[44:45] op_sel_hi:[1,0]
	v_cvt_pk_bf16_f32 v4, v8, v9
	v_cvt_pk_bf16_f32 v5, v10, v11
	v_cvt_pk_bf16_f32 v6, v12, v13
	v_cvt_pk_bf16_f32 v7, v14, v15
	s_nop 1
	v_permlane32_swap_b32_e32 v4, v6
	v_permlane32_swap_b32_e32 v5, v7
	global_store_dwordx4 v[124:125], v[4:7], off offset:96
	s_nop 1
	s_waitcnt lgkmcnt(12)
	v_mfma_f32_32x32x16_bf16 v[0:15], v[104:107], v[116:119], 0
	v_add_u32_e32 v40, v187, v205
	ds_read_b64_tr_b16 v[104:105], v186 offset:62848
	ds_read_b64_tr_b16 v[106:107], v40
	s_waitcnt lgkmcnt(12)
	v_mfma_f32_32x32x16_bf16 v[0:15], v[108:111], v[112:115], v[0:15]
	v_add_u32_e32 v40, v188, v205
	v_add_u32_e32 v42, v189, v205
	ds_read_b64_tr_b16 v[108:109], v40
	ds_read_b64_tr_b16 v[110:111], v42
	s_waitcnt lgkmcnt(12)
	v_mfma_f32_32x32x16_bf16 v[0:15], v[120:123], v[100:103], v[0:15]
	v_add_u32_e32 v40, v190, v205
	v_add_u32_e32 v42, v191, v205
	ds_read_b64_tr_b16 v[120:121], v40
	ds_read_b64_tr_b16 v[122:123], v42
	s_waitcnt lgkmcnt(12)
	v_mfma_f32_32x32x16_bf16 v[0:15], v[56:59], v[96:99], v[0:15]
	v_add_u32_e32 v40, v192, v205
	v_add_u32_e32 v42, v193, v205
	ds_read_b64_tr_b16 v[56:57], v40
	ds_read_b64_tr_b16 v[58:59], v42
	s_waitcnt lgkmcnt(12)
	v_mfma_f32_32x32x16_bf16 v[0:15], v[60:63], v[84:87], v[0:15]
	v_add_u32_e32 v40, v194, v205
	v_add_u32_e32 v42, v195, v205
	ds_read_b64_tr_b16 v[60:61], v40
	ds_read_b64_tr_b16 v[62:63], v42
	s_waitcnt lgkmcnt(12)
	v_mfma_f32_32x32x16_bf16 v[0:15], v[88:91], v[80:83], v[0:15]
	v_add_u32_e32 v40, v196, v205
	v_add_u32_e32 v42, v197, v205
	ds_read_b64_tr_b16 v[88:89], v40
	ds_read_b64_tr_b16 v[90:91], v42
	s_waitcnt lgkmcnt(12)
	v_mfma_f32_32x32x16_bf16 v[0:15], v[92:95], v[68:71], v[0:15]
	v_add_u32_e32 v40, v198, v205
	v_add_u32_e32 v42, v199, v205
	ds_read_b64_tr_b16 v[92:93], v40
	ds_read_b64_tr_b16 v[94:95], v42
	s_waitcnt lgkmcnt(12)
	v_mfma_f32_32x32x16_bf16 v[0:15], v[104:107], v[64:67], v[0:15]
	v_add_u32_e32 v40, v200, v205
	v_add_u32_e32 v42, v201, v205
	ds_read_b64_tr_b16 v[104:105], v40
	ds_read_b64_tr_b16 v[106:107], v42
	s_waitcnt lgkmcnt(12)
	v_mfma_f32_32x32x16_bf16 v[0:15], v[108:111], v[52:55], v[0:15]
	v_add_u32_e32 v40, v202, v205
	v_add_u32_e32 v42, v203, v205
	ds_read_b64_tr_b16 v[108:109], v40
	ds_read_b64_tr_b16 v[110:111], v42
	s_waitcnt lgkmcnt(12)
	v_mfma_f32_32x32x16_bf16 v[0:15], v[120:123], v[48:51], v[0:15]
	ds_read_b64_tr_b16 v[120:121], v186 offset:192
	ds_read_b64_tr_b16 v[122:123], v186 offset:4672
	s_waitcnt lgkmcnt(12)
	v_mfma_f32_32x32x16_bf16 v[0:15], v[56:59], v[36:39], v[0:15]
	ds_read_b64_tr_b16 v[56:57], v186 offset:9152
	ds_read_b64_tr_b16 v[58:59], v186 offset:13632
	s_waitcnt lgkmcnt(12)
	v_mfma_f32_32x32x16_bf16 v[0:15], v[60:63], v[32:35], v[0:15]
	ds_read_b64_tr_b16 v[60:61], v186 offset:18112
	ds_read_b64_tr_b16 v[62:63], v186 offset:22592
	s_waitcnt lgkmcnt(12)
	v_mfma_f32_32x32x16_bf16 v[0:15], v[88:91], v[20:23], v[0:15]
	ds_read_b64_tr_b16 v[88:89], v186 offset:27072
	ds_read_b64_tr_b16 v[90:91], v186 offset:31552
	s_waitcnt lgkmcnt(12)
	v_mfma_f32_32x32x16_bf16 v[0:15], v[92:95], v[16:19], v[0:15]
	ds_read_b64_tr_b16 v[92:93], v186 offset:36032
	ds_read_b64_tr_b16 v[94:95], v186 offset:40512
	s_waitcnt lgkmcnt(12)
	v_mfma_f32_32x32x16_bf16 v[0:15], v[104:107], v[28:31], v[0:15]
	ds_read_b64_tr_b16 v[104:105], v186 offset:44992
	ds_read_b64_tr_b16 v[106:107], v186 offset:49472
	s_waitcnt lgkmcnt(12)
	v_mfma_f32_32x32x16_bf16 v[0:15], v[108:111], v[24:27], v[0:15]
	ds_read_b64_tr_b16 v[108:109], v186 offset:53952
	ds_read_b64_tr_b16 v[110:111], v186 offset:58432
	s_nop 11
	v_pk_mul_f32 v[0:1], v[0:1], v[44:45] op_sel_hi:[1,0]
	v_pk_mul_f32 v[2:3], v[2:3], v[44:45] op_sel_hi:[1,0]
	v_pk_mul_f32 v[4:5], v[4:5], v[44:45] op_sel_hi:[1,0]
	v_pk_mul_f32 v[6:7], v[6:7], v[44:45] op_sel_hi:[1,0]
	v_cvt_pk_bf16_f32 v0, v0, v1
	v_cvt_pk_bf16_f32 v1, v2, v3
	v_cvt_pk_bf16_f32 v2, v4, v5
	v_cvt_pk_bf16_f32 v3, v6, v7
	s_nop 1
	v_permlane32_swap_b32_e32 v0, v2
	v_permlane32_swap_b32_e32 v1, v3
	global_store_dwordx4 v[124:125], v[0:3], off offset:128
	v_pk_mul_f32 v[8:9], v[8:9], v[44:45] op_sel_hi:[1,0]
	v_pk_mul_f32 v[10:11], v[10:11], v[44:45] op_sel_hi:[1,0]
	v_pk_mul_f32 v[12:13], v[12:13], v[44:45] op_sel_hi:[1,0]
	v_pk_mul_f32 v[14:15], v[14:15], v[44:45] op_sel_hi:[1,0]
	v_cvt_pk_bf16_f32 v4, v8, v9
	v_cvt_pk_bf16_f32 v5, v10, v11
	v_cvt_pk_bf16_f32 v6, v12, v13
	v_cvt_pk_bf16_f32 v7, v14, v15
	s_nop 1
	v_permlane32_swap_b32_e32 v4, v6
	v_permlane32_swap_b32_e32 v5, v7
	global_store_dwordx4 v[124:125], v[4:7], off offset:160
	s_nop 1
	s_waitcnt lgkmcnt(12)
	v_mfma_f32_32x32x16_bf16 v[0:15], v[120:123], v[116:119], 0
	v_add_u32_e32 v40, v187, v206
	ds_read_b64_tr_b16 v[120:121], v186 offset:62912
	ds_read_b64_tr_b16 v[122:123], v40
	s_waitcnt lgkmcnt(12)
	v_mfma_f32_32x32x16_bf16 v[0:15], v[56:59], v[112:115], v[0:15]
	v_add_u32_e32 v40, v188, v206
	v_add_u32_e32 v42, v189, v206
	ds_read_b64_tr_b16 v[56:57], v40
	ds_read_b64_tr_b16 v[58:59], v42
	s_waitcnt lgkmcnt(12)
	v_mfma_f32_32x32x16_bf16 v[0:15], v[60:63], v[100:103], v[0:15]
	v_add_u32_e32 v40, v190, v206
	v_add_u32_e32 v42, v191, v206
	ds_read_b64_tr_b16 v[60:61], v40
	ds_read_b64_tr_b16 v[62:63], v42
	s_waitcnt lgkmcnt(12)
	v_mfma_f32_32x32x16_bf16 v[0:15], v[88:91], v[96:99], v[0:15]
	v_add_u32_e32 v40, v192, v206
	v_add_u32_e32 v42, v193, v206
	ds_read_b64_tr_b16 v[88:89], v40
	ds_read_b64_tr_b16 v[90:91], v42
	s_waitcnt lgkmcnt(12)
	v_mfma_f32_32x32x16_bf16 v[0:15], v[92:95], v[84:87], v[0:15]
	v_add_u32_e32 v40, v194, v206
	v_add_u32_e32 v42, v195, v206
	ds_read_b64_tr_b16 v[92:93], v40
	ds_read_b64_tr_b16 v[94:95], v42
	s_waitcnt lgkmcnt(12)
	v_mfma_f32_32x32x16_bf16 v[0:15], v[104:107], v[80:83], v[0:15]
	v_add_u32_e32 v40, v196, v206
	v_add_u32_e32 v42, v197, v206
	ds_read_b64_tr_b16 v[104:105], v40
	ds_read_b64_tr_b16 v[106:107], v42
	s_waitcnt lgkmcnt(12)
	v_mfma_f32_32x32x16_bf16 v[0:15], v[108:111], v[68:71], v[0:15]
	v_add_u32_e32 v40, v198, v206
	v_add_u32_e32 v42, v199, v206
	ds_read_b64_tr_b16 v[108:109], v40
	ds_read_b64_tr_b16 v[110:111], v42
	s_waitcnt lgkmcnt(12)
	v_mfma_f32_32x32x16_bf16 v[0:15], v[120:123], v[64:67], v[0:15]
	v_add_u32_e32 v40, v200, v206
	v_add_u32_e32 v42, v201, v206
	ds_read_b64_tr_b16 v[120:121], v40
	ds_read_b64_tr_b16 v[122:123], v42
	s_waitcnt lgkmcnt(12)
	v_mfma_f32_32x32x16_bf16 v[0:15], v[56:59], v[52:55], v[0:15]
	v_add_u32_e32 v40, v202, v206
	v_add_u32_e32 v42, v203, v206
	ds_read_b64_tr_b16 v[56:57], v40
	ds_read_b64_tr_b16 v[58:59], v42
	s_waitcnt lgkmcnt(12)
	v_mfma_f32_32x32x16_bf16 v[0:15], v[60:63], v[48:51], v[0:15]
	ds_read_b64_tr_b16 v[60:61], v186 offset:256
	ds_read_b64_tr_b16 v[62:63], v186 offset:4736
	s_waitcnt lgkmcnt(12)
	v_mfma_f32_32x32x16_bf16 v[0:15], v[88:91], v[36:39], v[0:15]
	ds_read_b64_tr_b16 v[88:89], v186 offset:9216
	ds_read_b64_tr_b16 v[90:91], v186 offset:13696
	s_waitcnt lgkmcnt(12)
	v_mfma_f32_32x32x16_bf16 v[0:15], v[92:95], v[32:35], v[0:15]
	ds_read_b64_tr_b16 v[92:93], v186 offset:18176
	ds_read_b64_tr_b16 v[94:95], v186 offset:22656
	s_waitcnt lgkmcnt(12)
	v_mfma_f32_32x32x16_bf16 v[0:15], v[104:107], v[20:23], v[0:15]
	ds_read_b64_tr_b16 v[104:105], v186 offset:27136
	ds_read_b64_tr_b16 v[106:107], v186 offset:31616
	s_waitcnt lgkmcnt(12)
	v_mfma_f32_32x32x16_bf16 v[0:15], v[108:111], v[16:19], v[0:15]
	ds_read_b64_tr_b16 v[108:109], v186 offset:36096
	ds_read_b64_tr_b16 v[110:111], v186 offset:40576
	s_waitcnt lgkmcnt(12)
	v_mfma_f32_32x32x16_bf16 v[0:15], v[120:123], v[28:31], v[0:15]
	ds_read_b64_tr_b16 v[120:121], v186 offset:45056
	ds_read_b64_tr_b16 v[122:123], v186 offset:49536
	s_waitcnt lgkmcnt(12)
	v_mfma_f32_32x32x16_bf16 v[0:15], v[56:59], v[24:27], v[0:15]
	ds_read_b64_tr_b16 v[56:57], v186 offset:54016
	ds_read_b64_tr_b16 v[58:59], v186 offset:58496
	s_nop 11
	v_pk_mul_f32 v[0:1], v[0:1], v[44:45] op_sel_hi:[1,0]
	v_pk_mul_f32 v[2:3], v[2:3], v[44:45] op_sel_hi:[1,0]
	v_pk_mul_f32 v[4:5], v[4:5], v[44:45] op_sel_hi:[1,0]
	v_pk_mul_f32 v[6:7], v[6:7], v[44:45] op_sel_hi:[1,0]
	v_cvt_pk_bf16_f32 v0, v0, v1
	v_cvt_pk_bf16_f32 v1, v2, v3
	v_cvt_pk_bf16_f32 v2, v4, v5
	v_cvt_pk_bf16_f32 v3, v6, v7
	s_nop 1
	v_permlane32_swap_b32_e32 v0, v2
	v_permlane32_swap_b32_e32 v1, v3
	global_store_dwordx4 v[124:125], v[0:3], off offset:192
	v_pk_mul_f32 v[8:9], v[8:9], v[44:45] op_sel_hi:[1,0]
	v_pk_mul_f32 v[10:11], v[10:11], v[44:45] op_sel_hi:[1,0]
	v_pk_mul_f32 v[12:13], v[12:13], v[44:45] op_sel_hi:[1,0]
	v_pk_mul_f32 v[14:15], v[14:15], v[44:45] op_sel_hi:[1,0]
	v_cvt_pk_bf16_f32 v4, v8, v9
	v_cvt_pk_bf16_f32 v5, v10, v11
	v_cvt_pk_bf16_f32 v6, v12, v13
	v_cvt_pk_bf16_f32 v7, v14, v15
	s_nop 1
	v_permlane32_swap_b32_e32 v4, v6
	v_permlane32_swap_b32_e32 v5, v7
	global_store_dwordx4 v[124:125], v[4:7], off offset:224
	s_nop 1
	s_waitcnt lgkmcnt(12)
	v_mfma_f32_32x32x16_bf16 v[0:15], v[60:63], v[116:119], 0
	v_add_u32_e32 v40, v187, v207
	ds_read_b64_tr_b16 v[60:61], v186 offset:62976
	ds_read_b64_tr_b16 v[62:63], v40
	s_waitcnt lgkmcnt(12)
	v_mfma_f32_32x32x16_bf16 v[0:15], v[88:91], v[112:115], v[0:15]
	v_add_u32_e32 v40, v188, v207
	v_add_u32_e32 v42, v189, v207
	ds_read_b64_tr_b16 v[88:89], v40
	ds_read_b64_tr_b16 v[90:91], v42
	s_waitcnt lgkmcnt(12)
	v_mfma_f32_32x32x16_bf16 v[0:15], v[92:95], v[100:103], v[0:15]
	v_add_u32_e32 v40, v190, v207
	v_add_u32_e32 v42, v191, v207
	ds_read_b64_tr_b16 v[92:93], v40
	ds_read_b64_tr_b16 v[94:95], v42
	s_waitcnt lgkmcnt(12)
	v_mfma_f32_32x32x16_bf16 v[0:15], v[104:107], v[96:99], v[0:15]
	v_add_u32_e32 v40, v192, v207
	v_add_u32_e32 v42, v193, v207
	ds_read_b64_tr_b16 v[104:105], v40
	ds_read_b64_tr_b16 v[106:107], v42
	s_waitcnt lgkmcnt(12)
	v_mfma_f32_32x32x16_bf16 v[0:15], v[108:111], v[84:87], v[0:15]
	v_add_u32_e32 v40, v194, v207
	v_add_u32_e32 v42, v195, v207
	ds_read_b64_tr_b16 v[108:109], v40
	ds_read_b64_tr_b16 v[110:111], v42
	s_waitcnt lgkmcnt(12)
	v_mfma_f32_32x32x16_bf16 v[0:15], v[120:123], v[80:83], v[0:15]
	v_add_u32_e32 v40, v196, v207
	v_add_u32_e32 v42, v197, v207
	ds_read_b64_tr_b16 v[120:121], v40
	ds_read_b64_tr_b16 v[122:123], v42
	s_waitcnt lgkmcnt(12)
	v_mfma_f32_32x32x16_bf16 v[0:15], v[56:59], v[68:71], v[0:15]
	v_add_u32_e32 v40, v198, v207
	v_add_u32_e32 v42, v199, v207
	ds_read_b64_tr_b16 v[56:57], v40
	ds_read_b64_tr_b16 v[58:59], v42
	s_waitcnt lgkmcnt(12)
	v_mfma_f32_32x32x16_bf16 v[0:15], v[60:63], v[64:67], v[0:15]
	v_add_u32_e32 v40, v200, v207
	v_add_u32_e32 v42, v201, v207
	ds_read_b64_tr_b16 v[60:61], v40
	ds_read_b64_tr_b16 v[62:63], v42
	s_waitcnt lgkmcnt(12)
	v_mfma_f32_32x32x16_bf16 v[0:15], v[88:91], v[52:55], v[0:15]
	v_add_u32_e32 v40, v202, v207
	v_add_u32_e32 v42, v203, v207
	ds_read_b64_tr_b16 v[88:89], v40
	ds_read_b64_tr_b16 v[90:91], v42
	s_waitcnt lgkmcnt(12)
	v_mfma_f32_32x32x16_bf16 v[0:15], v[92:95], v[48:51], v[0:15]
	ds_read_b64_tr_b16 v[92:93], v186 offset:320
	ds_read_b64_tr_b16 v[94:95], v186 offset:4800
	s_waitcnt lgkmcnt(12)
	v_mfma_f32_32x32x16_bf16 v[0:15], v[104:107], v[36:39], v[0:15]
	ds_read_b64_tr_b16 v[104:105], v186 offset:9280
	ds_read_b64_tr_b16 v[106:107], v186 offset:13760
	s_waitcnt lgkmcnt(12)
	v_mfma_f32_32x32x16_bf16 v[0:15], v[108:111], v[32:35], v[0:15]
	ds_read_b64_tr_b16 v[108:109], v186 offset:18240
	ds_read_b64_tr_b16 v[110:111], v186 offset:22720
	s_waitcnt lgkmcnt(12)
	v_mfma_f32_32x32x16_bf16 v[0:15], v[120:123], v[20:23], v[0:15]
	ds_read_b64_tr_b16 v[120:121], v186 offset:27200
	ds_read_b64_tr_b16 v[122:123], v186 offset:31680
	s_waitcnt lgkmcnt(12)
	v_mfma_f32_32x32x16_bf16 v[0:15], v[56:59], v[16:19], v[0:15]
	ds_read_b64_tr_b16 v[56:57], v186 offset:36160
	ds_read_b64_tr_b16 v[58:59], v186 offset:40640
	s_waitcnt lgkmcnt(12)
	v_mfma_f32_32x32x16_bf16 v[0:15], v[60:63], v[28:31], v[0:15]
	ds_read_b64_tr_b16 v[60:61], v186 offset:45120
	ds_read_b64_tr_b16 v[62:63], v186 offset:49600
	s_waitcnt lgkmcnt(12)
	v_mfma_f32_32x32x16_bf16 v[0:15], v[88:91], v[24:27], v[0:15]
	ds_read_b64_tr_b16 v[88:89], v186 offset:54080
	ds_read_b64_tr_b16 v[90:91], v186 offset:58560
	s_nop 11
	v_pk_mul_f32 v[0:1], v[0:1], v[44:45] op_sel_hi:[1,0]
	v_pk_mul_f32 v[2:3], v[2:3], v[44:45] op_sel_hi:[1,0]
	v_pk_mul_f32 v[4:5], v[4:5], v[44:45] op_sel_hi:[1,0]
	v_pk_mul_f32 v[6:7], v[6:7], v[44:45] op_sel_hi:[1,0]
	v_cvt_pk_bf16_f32 v0, v0, v1
	v_cvt_pk_bf16_f32 v1, v2, v3
	v_cvt_pk_bf16_f32 v2, v4, v5
	v_cvt_pk_bf16_f32 v3, v6, v7
	s_nop 1
	v_permlane32_swap_b32_e32 v0, v2
	v_permlane32_swap_b32_e32 v1, v3
	global_store_dwordx4 v[124:125], v[0:3], off offset:256
	v_pk_mul_f32 v[8:9], v[8:9], v[44:45] op_sel_hi:[1,0]
	v_pk_mul_f32 v[10:11], v[10:11], v[44:45] op_sel_hi:[1,0]
	v_pk_mul_f32 v[12:13], v[12:13], v[44:45] op_sel_hi:[1,0]
	v_pk_mul_f32 v[14:15], v[14:15], v[44:45] op_sel_hi:[1,0]
	v_cvt_pk_bf16_f32 v4, v8, v9
	v_cvt_pk_bf16_f32 v5, v10, v11
	v_cvt_pk_bf16_f32 v6, v12, v13
	v_cvt_pk_bf16_f32 v7, v14, v15
	s_nop 1
	v_permlane32_swap_b32_e32 v4, v6
	v_permlane32_swap_b32_e32 v5, v7
	global_store_dwordx4 v[124:125], v[4:7], off offset:288
	s_nop 1
	s_waitcnt lgkmcnt(12)
	v_mfma_f32_32x32x16_bf16 v[0:15], v[92:95], v[116:119], 0
	v_add_u32_e32 v40, v187, v208
	ds_read_b64_tr_b16 v[92:93], v186 offset:63040
	ds_read_b64_tr_b16 v[94:95], v40
	s_waitcnt lgkmcnt(12)
	v_mfma_f32_32x32x16_bf16 v[0:15], v[104:107], v[112:115], v[0:15]
	v_add_u32_e32 v40, v188, v208
	v_add_u32_e32 v42, v189, v208
	ds_read_b64_tr_b16 v[104:105], v40
	ds_read_b64_tr_b16 v[106:107], v42
	s_waitcnt lgkmcnt(12)
	v_mfma_f32_32x32x16_bf16 v[0:15], v[108:111], v[100:103], v[0:15]
	v_add_u32_e32 v40, v190, v208
	v_add_u32_e32 v42, v191, v208
	ds_read_b64_tr_b16 v[108:109], v40
	ds_read_b64_tr_b16 v[110:111], v42
	s_waitcnt lgkmcnt(12)
	v_mfma_f32_32x32x16_bf16 v[0:15], v[120:123], v[96:99], v[0:15]
	v_add_u32_e32 v40, v192, v208
	v_add_u32_e32 v42, v193, v208
	ds_read_b64_tr_b16 v[120:121], v40
	ds_read_b64_tr_b16 v[122:123], v42
	s_waitcnt lgkmcnt(12)
	v_mfma_f32_32x32x16_bf16 v[0:15], v[56:59], v[84:87], v[0:15]
	v_add_u32_e32 v40, v194, v208
	v_add_u32_e32 v42, v195, v208
	ds_read_b64_tr_b16 v[56:57], v40
	ds_read_b64_tr_b16 v[58:59], v42
	s_waitcnt lgkmcnt(12)
	v_mfma_f32_32x32x16_bf16 v[0:15], v[60:63], v[80:83], v[0:15]
	v_add_u32_e32 v40, v196, v208
	v_add_u32_e32 v42, v197, v208
	ds_read_b64_tr_b16 v[60:61], v40
	ds_read_b64_tr_b16 v[62:63], v42
	s_waitcnt lgkmcnt(12)
	v_mfma_f32_32x32x16_bf16 v[0:15], v[88:91], v[68:71], v[0:15]
	v_add_u32_e32 v40, v198, v208
	v_add_u32_e32 v42, v199, v208
	ds_read_b64_tr_b16 v[88:89], v40
	ds_read_b64_tr_b16 v[90:91], v42
	s_waitcnt lgkmcnt(12)
	v_mfma_f32_32x32x16_bf16 v[0:15], v[92:95], v[64:67], v[0:15]
	v_add_u32_e32 v40, v200, v208
	v_add_u32_e32 v42, v201, v208
	ds_read_b64_tr_b16 v[92:93], v40
	ds_read_b64_tr_b16 v[94:95], v42
	s_waitcnt lgkmcnt(12)
	v_mfma_f32_32x32x16_bf16 v[0:15], v[104:107], v[52:55], v[0:15]
	v_add_u32_e32 v40, v202, v208
	v_add_u32_e32 v42, v203, v208
	ds_read_b64_tr_b16 v[104:105], v40
	ds_read_b64_tr_b16 v[106:107], v42
	s_waitcnt lgkmcnt(12)
	v_mfma_f32_32x32x16_bf16 v[0:15], v[108:111], v[48:51], v[0:15]
	ds_read_b64_tr_b16 v[108:109], v186 offset:384
	ds_read_b64_tr_b16 v[110:111], v186 offset:4864
	s_waitcnt lgkmcnt(12)
	v_mfma_f32_32x32x16_bf16 v[0:15], v[120:123], v[36:39], v[0:15]
	ds_read_b64_tr_b16 v[120:121], v186 offset:9344
	ds_read_b64_tr_b16 v[122:123], v186 offset:13824
	s_waitcnt lgkmcnt(12)
	v_mfma_f32_32x32x16_bf16 v[0:15], v[56:59], v[32:35], v[0:15]
	ds_read_b64_tr_b16 v[56:57], v186 offset:18304
	ds_read_b64_tr_b16 v[58:59], v186 offset:22784
	s_waitcnt lgkmcnt(12)
	v_mfma_f32_32x32x16_bf16 v[0:15], v[60:63], v[20:23], v[0:15]
	ds_read_b64_tr_b16 v[60:61], v186 offset:27264
	ds_read_b64_tr_b16 v[62:63], v186 offset:31744
	s_waitcnt lgkmcnt(12)
	v_mfma_f32_32x32x16_bf16 v[0:15], v[88:91], v[16:19], v[0:15]
	ds_read_b64_tr_b16 v[88:89], v186 offset:36224
	ds_read_b64_tr_b16 v[90:91], v186 offset:40704
	s_waitcnt lgkmcnt(12)
	v_mfma_f32_32x32x16_bf16 v[0:15], v[92:95], v[28:31], v[0:15]
	ds_read_b64_tr_b16 v[92:93], v186 offset:45184
	ds_read_b64_tr_b16 v[94:95], v186 offset:49664
	s_waitcnt lgkmcnt(12)
	v_mfma_f32_32x32x16_bf16 v[0:15], v[104:107], v[24:27], v[0:15]
	ds_read_b64_tr_b16 v[104:105], v186 offset:54144
	ds_read_b64_tr_b16 v[106:107], v186 offset:58624
	s_nop 11
	v_pk_mul_f32 v[0:1], v[0:1], v[44:45] op_sel_hi:[1,0]
	v_pk_mul_f32 v[2:3], v[2:3], v[44:45] op_sel_hi:[1,0]
	v_pk_mul_f32 v[4:5], v[4:5], v[44:45] op_sel_hi:[1,0]
	v_pk_mul_f32 v[6:7], v[6:7], v[44:45] op_sel_hi:[1,0]
	v_cvt_pk_bf16_f32 v0, v0, v1
	v_cvt_pk_bf16_f32 v1, v2, v3
	v_cvt_pk_bf16_f32 v2, v4, v5
	v_cvt_pk_bf16_f32 v3, v6, v7
	s_nop 1
	v_permlane32_swap_b32_e32 v0, v2
	v_permlane32_swap_b32_e32 v1, v3
	global_store_dwordx4 v[124:125], v[0:3], off offset:320
	v_pk_mul_f32 v[8:9], v[8:9], v[44:45] op_sel_hi:[1,0]
	v_pk_mul_f32 v[10:11], v[10:11], v[44:45] op_sel_hi:[1,0]
	v_pk_mul_f32 v[12:13], v[12:13], v[44:45] op_sel_hi:[1,0]
	v_pk_mul_f32 v[14:15], v[14:15], v[44:45] op_sel_hi:[1,0]
	v_cvt_pk_bf16_f32 v4, v8, v9
	v_cvt_pk_bf16_f32 v5, v10, v11
	v_cvt_pk_bf16_f32 v6, v12, v13
	v_cvt_pk_bf16_f32 v7, v14, v15
	s_nop 1
	v_permlane32_swap_b32_e32 v4, v6
	v_permlane32_swap_b32_e32 v5, v7
	global_store_dwordx4 v[124:125], v[4:7], off offset:352
	s_nop 1
	s_waitcnt lgkmcnt(12)
	v_mfma_f32_32x32x16_bf16 v[0:15], v[108:111], v[116:119], 0
	v_add_u32_e32 v40, v187, v209
	ds_read_b64_tr_b16 v[108:109], v186 offset:63104
	ds_read_b64_tr_b16 v[110:111], v40
	s_waitcnt lgkmcnt(12)
	v_mfma_f32_32x32x16_bf16 v[0:15], v[120:123], v[112:115], v[0:15]
	v_add_u32_e32 v40, v188, v209
	v_add_u32_e32 v42, v189, v209
	ds_read_b64_tr_b16 v[120:121], v40
	ds_read_b64_tr_b16 v[122:123], v42
	s_waitcnt lgkmcnt(12)
	v_mfma_f32_32x32x16_bf16 v[0:15], v[56:59], v[100:103], v[0:15]
	v_add_u32_e32 v40, v190, v209
	v_add_u32_e32 v42, v191, v209
	ds_read_b64_tr_b16 v[56:57], v40
	ds_read_b64_tr_b16 v[58:59], v42
	s_waitcnt lgkmcnt(12)
	v_mfma_f32_32x32x16_bf16 v[0:15], v[60:63], v[96:99], v[0:15]
	v_add_u32_e32 v40, v192, v209
	v_add_u32_e32 v42, v193, v209
	ds_read_b64_tr_b16 v[60:61], v40
	ds_read_b64_tr_b16 v[62:63], v42
	s_waitcnt lgkmcnt(12)
	v_mfma_f32_32x32x16_bf16 v[0:15], v[88:91], v[84:87], v[0:15]
	v_add_u32_e32 v40, v194, v209
	v_add_u32_e32 v42, v195, v209
	ds_read_b64_tr_b16 v[88:89], v40
	ds_read_b64_tr_b16 v[90:91], v42
	s_waitcnt lgkmcnt(12)
	v_mfma_f32_32x32x16_bf16 v[0:15], v[92:95], v[80:83], v[0:15]
	v_add_u32_e32 v40, v196, v209
	v_add_u32_e32 v42, v197, v209
	ds_read_b64_tr_b16 v[92:93], v40
	ds_read_b64_tr_b16 v[94:95], v42
	s_waitcnt lgkmcnt(12)
	v_mfma_f32_32x32x16_bf16 v[0:15], v[104:107], v[68:71], v[0:15]
	v_add_u32_e32 v40, v198, v209
	v_add_u32_e32 v42, v199, v209
	ds_read_b64_tr_b16 v[104:105], v40
	ds_read_b64_tr_b16 v[106:107], v42
	s_waitcnt lgkmcnt(12)
	v_mfma_f32_32x32x16_bf16 v[0:15], v[108:111], v[64:67], v[0:15]
	v_add_u32_e32 v40, v200, v209
	v_add_u32_e32 v42, v201, v209
	ds_read_b64_tr_b16 v[108:109], v40
	ds_read_b64_tr_b16 v[110:111], v42
	s_waitcnt lgkmcnt(12)
	v_mfma_f32_32x32x16_bf16 v[0:15], v[120:123], v[52:55], v[0:15]
	v_add_u32_e32 v40, v202, v209
	v_add_u32_e32 v42, v203, v209
	ds_read_b64_tr_b16 v[120:121], v40
	ds_read_b64_tr_b16 v[122:123], v42
	s_waitcnt lgkmcnt(12)
	v_mfma_f32_32x32x16_bf16 v[0:15], v[56:59], v[48:51], v[0:15]
	ds_read_b64_tr_b16 v[56:57], v186 offset:448
	ds_read_b64_tr_b16 v[58:59], v186 offset:4928
	s_waitcnt lgkmcnt(12)
	v_mfma_f32_32x32x16_bf16 v[0:15], v[60:63], v[36:39], v[0:15]
	ds_read_b64_tr_b16 v[60:61], v186 offset:9408
	ds_read_b64_tr_b16 v[62:63], v186 offset:13888
	s_waitcnt lgkmcnt(12)
	v_mfma_f32_32x32x16_bf16 v[0:15], v[88:91], v[32:35], v[0:15]
	ds_read_b64_tr_b16 v[88:89], v186 offset:18368
	ds_read_b64_tr_b16 v[90:91], v186 offset:22848
	s_waitcnt lgkmcnt(12)
	v_mfma_f32_32x32x16_bf16 v[0:15], v[92:95], v[20:23], v[0:15]
	ds_read_b64_tr_b16 v[92:93], v186 offset:27328
	ds_read_b64_tr_b16 v[94:95], v186 offset:31808
	s_waitcnt lgkmcnt(12)
	v_mfma_f32_32x32x16_bf16 v[0:15], v[104:107], v[16:19], v[0:15]
	ds_read_b64_tr_b16 v[104:105], v186 offset:36288
	ds_read_b64_tr_b16 v[106:107], v186 offset:40768
	s_waitcnt lgkmcnt(12)
	v_mfma_f32_32x32x16_bf16 v[0:15], v[108:111], v[28:31], v[0:15]
	ds_read_b64_tr_b16 v[108:109], v186 offset:45248
	ds_read_b64_tr_b16 v[110:111], v186 offset:49728
	s_waitcnt lgkmcnt(12)
	v_mfma_f32_32x32x16_bf16 v[0:15], v[120:123], v[24:27], v[0:15]
	ds_read_b64_tr_b16 v[120:121], v186 offset:54208
	ds_read_b64_tr_b16 v[122:123], v186 offset:58688
	s_nop 11
	v_pk_mul_f32 v[0:1], v[0:1], v[44:45] op_sel_hi:[1,0]
	v_pk_mul_f32 v[2:3], v[2:3], v[44:45] op_sel_hi:[1,0]
	v_pk_mul_f32 v[4:5], v[4:5], v[44:45] op_sel_hi:[1,0]
	v_pk_mul_f32 v[6:7], v[6:7], v[44:45] op_sel_hi:[1,0]
	v_cvt_pk_bf16_f32 v0, v0, v1
	v_cvt_pk_bf16_f32 v1, v2, v3
	v_cvt_pk_bf16_f32 v2, v4, v5
	v_cvt_pk_bf16_f32 v3, v6, v7
	s_nop 1
	v_permlane32_swap_b32_e32 v0, v2
	v_permlane32_swap_b32_e32 v1, v3
	global_store_dwordx4 v[124:125], v[0:3], off offset:384
	v_pk_mul_f32 v[8:9], v[8:9], v[44:45] op_sel_hi:[1,0]
	v_pk_mul_f32 v[10:11], v[10:11], v[44:45] op_sel_hi:[1,0]
	v_pk_mul_f32 v[12:13], v[12:13], v[44:45] op_sel_hi:[1,0]
	v_pk_mul_f32 v[14:15], v[14:15], v[44:45] op_sel_hi:[1,0]
	v_cvt_pk_bf16_f32 v4, v8, v9
	v_cvt_pk_bf16_f32 v5, v10, v11
	v_cvt_pk_bf16_f32 v6, v12, v13
	v_cvt_pk_bf16_f32 v7, v14, v15
	s_nop 1
	v_permlane32_swap_b32_e32 v4, v6
	v_permlane32_swap_b32_e32 v5, v7
	global_store_dwordx4 v[124:125], v[4:7], off offset:416
	s_nop 1
	s_waitcnt lgkmcnt(12)
	v_mfma_f32_32x32x16_bf16 v[0:15], v[56:59], v[116:119], 0
	v_add_u32_e32 v40, v187, v210
	ds_read_b64_tr_b16 v[56:57], v186 offset:63168
	ds_read_b64_tr_b16 v[58:59], v40
	s_waitcnt lgkmcnt(12)
	v_mfma_f32_32x32x16_bf16 v[0:15], v[60:63], v[112:115], v[0:15]
	v_add_u32_e32 v40, v188, v210
	v_add_u32_e32 v42, v189, v210
	ds_read_b64_tr_b16 v[60:61], v40
	ds_read_b64_tr_b16 v[62:63], v42
	s_waitcnt lgkmcnt(12)
	v_mfma_f32_32x32x16_bf16 v[0:15], v[88:91], v[100:103], v[0:15]
	v_add_u32_e32 v40, v190, v210
	v_add_u32_e32 v42, v191, v210
	ds_read_b64_tr_b16 v[88:89], v40
	ds_read_b64_tr_b16 v[90:91], v42
	s_waitcnt lgkmcnt(12)
	v_mfma_f32_32x32x16_bf16 v[0:15], v[92:95], v[96:99], v[0:15]
	v_add_u32_e32 v40, v192, v210
	v_add_u32_e32 v42, v193, v210
	ds_read_b64_tr_b16 v[92:93], v40
	ds_read_b64_tr_b16 v[94:95], v42
	s_waitcnt lgkmcnt(12)
	v_mfma_f32_32x32x16_bf16 v[0:15], v[104:107], v[84:87], v[0:15]
	v_add_u32_e32 v40, v194, v210
	v_add_u32_e32 v42, v195, v210
	ds_read_b64_tr_b16 v[104:105], v40
	ds_read_b64_tr_b16 v[106:107], v42
	s_waitcnt lgkmcnt(12)
	v_mfma_f32_32x32x16_bf16 v[0:15], v[108:111], v[80:83], v[0:15]
	v_add_u32_e32 v40, v196, v210
	v_add_u32_e32 v42, v197, v210
	ds_read_b64_tr_b16 v[108:109], v40
	ds_read_b64_tr_b16 v[110:111], v42
	s_waitcnt lgkmcnt(12)
	v_mfma_f32_32x32x16_bf16 v[0:15], v[120:123], v[68:71], v[0:15]
	v_add_u32_e32 v40, v198, v210
	v_add_u32_e32 v42, v199, v210
	ds_read_b64_tr_b16 v[120:121], v40
	ds_read_b64_tr_b16 v[122:123], v42
	s_waitcnt lgkmcnt(12)
	v_mfma_f32_32x32x16_bf16 v[0:15], v[56:59], v[64:67], v[0:15]
	v_add_u32_e32 v40, v200, v210
	v_add_u32_e32 v42, v201, v210
	ds_read_b64_tr_b16 v[56:57], v40
	ds_read_b64_tr_b16 v[58:59], v42
	s_waitcnt lgkmcnt(12)
	v_mfma_f32_32x32x16_bf16 v[0:15], v[60:63], v[52:55], v[0:15]
	v_add_u32_e32 v40, v202, v210
	v_add_u32_e32 v42, v203, v210
	ds_read_b64_tr_b16 v[60:61], v40
	ds_read_b64_tr_b16 v[62:63], v42
	s_waitcnt lgkmcnt(12)
	v_mfma_f32_32x32x16_bf16 v[0:15], v[88:91], v[48:51], v[0:15]
	s_waitcnt lgkmcnt(10)
	v_mfma_f32_32x32x16_bf16 v[0:15], v[92:95], v[36:39], v[0:15]
	s_waitcnt lgkmcnt(8)
	v_mfma_f32_32x32x16_bf16 v[0:15], v[104:107], v[32:35], v[0:15]
	s_waitcnt lgkmcnt(6)
	v_mfma_f32_32x32x16_bf16 v[0:15], v[108:111], v[20:23], v[0:15]
	s_waitcnt lgkmcnt(4)
	v_mfma_f32_32x32x16_bf16 v[0:15], v[120:123], v[16:19], v[0:15]
	s_waitcnt lgkmcnt(2)
	v_mfma_f32_32x32x16_bf16 v[0:15], v[56:59], v[28:31], v[0:15]
	s_waitcnt lgkmcnt(0)
	v_mfma_f32_32x32x16_bf16 v[0:15], v[60:63], v[24:27], v[0:15]
	s_nop 11
	v_pk_mul_f32 v[0:1], v[0:1], v[44:45] op_sel_hi:[1,0]
	v_pk_mul_f32 v[2:3], v[2:3], v[44:45] op_sel_hi:[1,0]
	v_pk_mul_f32 v[4:5], v[4:5], v[44:45] op_sel_hi:[1,0]
	v_pk_mul_f32 v[6:7], v[6:7], v[44:45] op_sel_hi:[1,0]
	v_cvt_pk_bf16_f32 v0, v0, v1
	v_cvt_pk_bf16_f32 v1, v2, v3
	v_cvt_pk_bf16_f32 v2, v4, v5
	v_cvt_pk_bf16_f32 v3, v6, v7
	s_nop 1
	v_permlane32_swap_b32_e32 v0, v2
	v_permlane32_swap_b32_e32 v1, v3
	global_store_dwordx4 v[124:125], v[0:3], off offset:448
	v_pk_mul_f32 v[8:9], v[8:9], v[44:45] op_sel_hi:[1,0]
	v_pk_mul_f32 v[10:11], v[10:11], v[44:45] op_sel_hi:[1,0]
	v_pk_mul_f32 v[12:13], v[12:13], v[44:45] op_sel_hi:[1,0]
	v_pk_mul_f32 v[14:15], v[14:15], v[44:45] op_sel_hi:[1,0]
	v_cvt_pk_bf16_f32 v4, v8, v9
	v_cvt_pk_bf16_f32 v5, v10, v11
	v_cvt_pk_bf16_f32 v6, v12, v13
	v_cvt_pk_bf16_f32 v7, v14, v15
	s_nop 1
	v_permlane32_swap_b32_e32 v4, v6
	v_permlane32_swap_b32_e32 v5, v7
	global_store_dwordx4 v[124:125], v[4:7], off offset:480
	s_nop 1
	s_barrier
	s_branch .LBB0_751
